# E4e + GEMM K-loops: the inner s_setprio 0 / s_setprio 1 flip between the two 16-MFMA groups of every super-phase deleted (36 pairs)
# baseline (speedup 1.0000x reference)
.LBB0_253:
	s_add_i32 s37, s6, 2
	s_add_u32 s58, s4, 0x80
	s_addc_u32 s7, s5, 0
	s_add_i32 s66, 0, 0x10000
	s_cmp_eq_u32 s62, s6
	s_cselect_b32 s7, s55, s7
	s_cselect_b32 s6, s54, s58
	v_add_u32_e32 v112, s66, v188
	s_cselect_b32 s59, s57, s36
	s_cselect_b32 s58, s56, s31
	s_add_i32 s67, 0, 0x14000
	ds_read_b128 v[136:139], v112
	ds_read_b128 v[140:143], v112 offset:1024
	ds_read_b128 v[144:147], v112 offset:2048
	ds_read_b128 v[148:151], v112 offset:3072
	v_add_u32_e32 v112, s67, v188
	ds_read_b128 v[152:155], v112
	ds_read_b128 v[156:159], v112 offset:1024
	ds_read_b128 v[160:163], v112 offset:2048
	ds_read_b128 v[164:167], v112 offset:3072
	v_lshl_add_u64 v[114:115], s[4:5], 0, v[178:179]
	s_add_i32 m0, s28, 0xc000
	ds_read_b128 v[192:195], v190
	ds_read_b128 v[196:199], v190 offset:1024
	ds_read_b128 v[200:203], v190 offset:2048
	ds_read_b128 v[208:211], v190 offset:3072
	ds_read_b128 v[212:215], v190 offset:4096
	ds_read_b128 v[216:219], v190 offset:5120
	ds_read_b128 v[220:223], v190 offset:6144
	ds_read_b128 v[224:227], v190 offset:7168
	global_load_lds_dwordx4 v[114:115], off
	v_lshl_add_u64 v[114:115], s[4:5], 0, v[180:181]
	s_add_i32 m0, s28, 0xe000
	s_nop 0
	global_load_lds_dwordx4 v[114:115], off
	s_waitcnt vmcnt(8)
	s_waitcnt lgkmcnt(0)
	s_barrier
	s_setprio 1
	s_waitcnt lgkmcnt(0)
	v_mfma_f32_16x16x32_bf16 v[132:135], v[136:139], v[192:195], v[132:135]
	v_mfma_f32_16x16x32_bf16 v[128:131], v[144:147], v[192:195], v[128:131]
	v_mfma_f32_16x16x32_bf16 v[114:117], v[136:139], v[200:203], v[116:119]
	v_mfma_f32_16x16x32_bf16 v[106:109], v[144:147], v[200:203], v[106:109]
	v_mfma_f32_16x16x32_bf16 v[94:97], v[136:139], v[212:215], v[94:97]
	v_mfma_f32_16x16x32_bf16 v[90:93], v[144:147], v[212:215], v[90:93]
	v_mfma_f32_16x16x32_bf16 v[78:81], v[136:139], v[220:223], v[78:81]
	v_mfma_f32_16x16x32_bf16 v[74:77], v[144:147], v[220:223], v[74:77]
	v_mfma_f32_16x16x32_bf16 v[132:135], v[140:143], v[196:199], v[132:135]
	v_mfma_f32_16x16x32_bf16 v[128:131], v[148:151], v[196:199], v[128:131]
	v_mfma_f32_16x16x32_bf16 v[114:117], v[140:143], v[208:211], v[114:117]
	v_mfma_f32_16x16x32_bf16 v[106:109], v[148:151], v[208:211], v[106:109]
	v_mfma_f32_16x16x32_bf16 v[94:97], v[140:143], v[216:219], v[94:97]
	v_mfma_f32_16x16x32_bf16 v[90:93], v[148:151], v[216:219], v[90:93]
	v_mfma_f32_16x16x32_bf16 v[78:81], v[140:143], v[224:227], v[78:81]
	v_mfma_f32_16x16x32_bf16 v[74:77], v[148:151], v[224:227], v[74:77]
	v_mfma_f32_16x16x32_bf16 v[124:127], v[152:155], v[192:195], v[124:127]
	v_mfma_f32_16x16x32_bf16 v[118:121], v[160:163], v[192:195], v[120:123]
	v_mfma_f32_16x16x32_bf16 v[102:105], v[152:155], v[200:203], v[102:105]
	v_mfma_f32_16x16x32_bf16 v[98:101], v[160:163], v[200:203], v[98:101]
	v_mfma_f32_16x16x32_bf16 v[86:89], v[152:155], v[212:215], v[86:89]
	v_mfma_f32_16x16x32_bf16 v[82:85], v[160:163], v[212:215], v[82:85]
	v_mfma_f32_16x16x32_bf16 v[70:73], v[152:155], v[220:223], v[70:73]
	v_mfma_f32_16x16x32_bf16 v[66:69], v[160:163], v[220:223], v[66:69]
	v_mfma_f32_16x16x32_bf16 v[124:127], v[156:159], v[196:199], v[124:127]
	v_mfma_f32_16x16x32_bf16 v[120:123], v[164:167], v[196:199], v[118:121]
	v_mfma_f32_16x16x32_bf16 v[102:105], v[156:159], v[208:211], v[102:105]
	v_mfma_f32_16x16x32_bf16 v[98:101], v[164:167], v[208:211], v[98:101]
	v_mfma_f32_16x16x32_bf16 v[86:89], v[156:159], v[216:219], v[86:89]
	v_mfma_f32_16x16x32_bf16 v[82:85], v[164:167], v[216:219], v[82:85]
	v_mfma_f32_16x16x32_bf16 v[70:73], v[156:159], v[224:227], v[70:73]
	v_mfma_f32_16x16x32_bf16 v[66:69], v[164:167], v[224:227], v[66:69]
	s_setprio 0
	s_barrier
	s_add_i32 s66, s66, s27
	v_lshl_add_u64 v[204:205], s[58:59], 0, v[174:175]
	s_mov_b32 m0, s66
	ds_read_b128 v[192:195], v190 offset:16384
	ds_read_b128 v[196:199], v190 offset:17408
	ds_read_b128 v[200:203], v190 offset:18432
	ds_read_b128 v[208:211], v190 offset:19456
	ds_read_b128 v[212:215], v190 offset:20480
	ds_read_b128 v[216:219], v190 offset:21504
	ds_read_b128 v[220:223], v190 offset:22528
	ds_read_b128 v[224:227], v190 offset:23552
	global_load_lds_dwordx4 v[204:205], off
	s_add_i32 m0, s66, 0x2000
	v_lshl_add_u64 v[228:229], s[58:59], 0, v[110:111]
	s_add_u32 s58, s58, s10
	s_addc_u32 s59, s59, s11
	s_add_i32 s66, s67, s27
	global_load_lds_dwordx4 v[228:229], off
	v_lshl_add_u64 v[230:231], s[58:59], 0, v[174:175]
	s_mov_b32 m0, s66
	v_lshl_add_u64 v[232:233], s[58:59], 0, v[110:111]
	global_load_lds_dwordx4 v[230:231], off
	s_add_i32 m0, s66, 0x2000
	v_lshl_add_u64 v[234:235], s[6:7], 0, v[176:177]
	global_load_lds_dwordx4 v[232:233], off
	s_mov_b32 m0, s28
	v_lshl_add_u64 v[236:237], s[6:7], 0, v[172:173]
	global_load_lds_dwordx4 v[234:235], off
	s_mov_b32 m0, s29
	s_nop 0
	global_load_lds_dwordx4 v[236:237], off
	s_waitcnt vmcnt(8)
	s_waitcnt lgkmcnt(0)
	s_barrier
	s_setprio 1
	s_waitcnt lgkmcnt(0)
	v_mfma_f32_16x16x32_bf16 v[62:65], v[136:139], v[192:195], v[62:65]
	v_mfma_f32_16x16x32_bf16 v[58:61], v[144:147], v[192:195], v[58:61]
	v_mfma_f32_16x16x32_bf16 v[46:49], v[136:139], v[200:203], v[46:49]
	v_mfma_f32_16x16x32_bf16 v[42:45], v[144:147], v[200:203], v[42:45]
	v_mfma_f32_16x16x32_bf16 v[30:33], v[136:139], v[212:215], v[30:33]
	v_mfma_f32_16x16x32_bf16 v[26:29], v[144:147], v[212:215], v[26:29]
	v_mfma_f32_16x16x32_bf16 v[14:17], v[136:139], v[220:223], v[14:17]
	v_mfma_f32_16x16x32_bf16 v[10:13], v[144:147], v[220:223], v[10:13]
	v_mfma_f32_16x16x32_bf16 v[62:65], v[140:143], v[196:199], v[62:65]
	v_mfma_f32_16x16x32_bf16 v[58:61], v[148:151], v[196:199], v[58:61]
	v_mfma_f32_16x16x32_bf16 v[46:49], v[140:143], v[208:211], v[46:49]
	v_mfma_f32_16x16x32_bf16 v[42:45], v[148:151], v[208:211], v[42:45]
	v_mfma_f32_16x16x32_bf16 v[30:33], v[140:143], v[216:219], v[30:33]
	v_mfma_f32_16x16x32_bf16 v[26:29], v[148:151], v[216:219], v[26:29]
	v_mfma_f32_16x16x32_bf16 v[14:17], v[140:143], v[224:227], v[14:17]
	v_mfma_f32_16x16x32_bf16 v[10:13], v[148:151], v[224:227], v[10:13]
	v_mfma_f32_16x16x32_bf16 v[54:57], v[152:155], v[192:195], v[54:57]
	v_mfma_f32_16x16x32_bf16 v[50:53], v[160:163], v[192:195], v[50:53]
	v_mfma_f32_16x16x32_bf16 v[38:41], v[152:155], v[200:203], v[38:41]
	v_mfma_f32_16x16x32_bf16 v[34:37], v[160:163], v[200:203], v[34:37]
	v_mfma_f32_16x16x32_bf16 v[22:25], v[152:155], v[212:215], v[22:25]
	v_mfma_f32_16x16x32_bf16 v[18:21], v[160:163], v[212:215], v[18:21]
	v_mfma_f32_16x16x32_bf16 v[6:9], v[152:155], v[220:223], v[6:9]
	v_mfma_f32_16x16x32_bf16 v[2:5], v[160:163], v[220:223], v[2:5]
	v_mfma_f32_16x16x32_bf16 v[54:57], v[156:159], v[196:199], v[54:57]
	v_mfma_f32_16x16x32_bf16 v[50:53], v[164:167], v[196:199], v[50:53]
	v_mfma_f32_16x16x32_bf16 v[38:41], v[156:159], v[208:211], v[38:41]
	v_mfma_f32_16x16x32_bf16 v[34:37], v[164:167], v[208:211], v[34:37]
	v_mfma_f32_16x16x32_bf16 v[22:25], v[156:159], v[216:219], v[22:25]
	v_mfma_f32_16x16x32_bf16 v[18:21], v[164:167], v[216:219], v[18:21]
	v_mfma_f32_16x16x32_bf16 v[6:9], v[156:159], v[224:227], v[6:9]
	v_mfma_f32_16x16x32_bf16 v[2:5], v[164:167], v[224:227], v[2:5]
	s_setprio 0
	s_barrier
	s_add_i32 s58, 0, 0x18000
	v_add_u32_e32 v112, s58, v188
	s_add_i32 s59, 0, 0x1c000
	ds_read_b128 v[136:139], v112
	ds_read_b128 v[140:143], v112 offset:1024
	ds_read_b128 v[144:147], v112 offset:2048
	ds_read_b128 v[148:151], v112 offset:3072
	v_add_u32_e32 v112, s59, v188
	ds_read_b128 v[152:155], v112
	ds_read_b128 v[156:159], v112 offset:1024
	ds_read_b128 v[160:163], v112 offset:2048
	ds_read_b128 v[164:167], v112 offset:3072
	s_add_u32 s6, s6, s10
	s_addc_u32 s7, s7, s11
	s_mov_b32 m0, s34
	v_lshl_add_u64 v[118:119], s[6:7], 0, v[176:177]
	ds_read_b128 v[192:195], v190 offset:32768
	ds_read_b128 v[196:199], v190 offset:33792
	ds_read_b128 v[200:203], v190 offset:34816
	ds_read_b128 v[208:211], v190 offset:35840
	ds_read_b128 v[212:215], v190 offset:36864
	ds_read_b128 v[216:219], v190 offset:37888
	ds_read_b128 v[220:223], v190 offset:38912
	ds_read_b128 v[224:227], v190 offset:39936
	global_load_lds_dwordx4 v[118:119], off
	v_lshl_add_u64 v[118:119], s[6:7], 0, v[172:173]
	s_mov_b32 m0, s44
	s_nop 0
	global_load_lds_dwordx4 v[118:119], off
	s_waitcnt vmcnt(8)
	s_waitcnt lgkmcnt(0)
	s_barrier
	s_setprio 1
	s_waitcnt lgkmcnt(0)
	v_mfma_f32_16x16x32_bf16 v[132:135], v[136:139], v[192:195], v[132:135]
	v_mfma_f32_16x16x32_bf16 v[128:131], v[144:147], v[192:195], v[128:131]
	v_mfma_f32_16x16x32_bf16 v[114:117], v[136:139], v[200:203], v[114:117]
	v_mfma_f32_16x16x32_bf16 v[106:109], v[144:147], v[200:203], v[106:109]
	v_mfma_f32_16x16x32_bf16 v[94:97], v[136:139], v[212:215], v[94:97]
	v_mfma_f32_16x16x32_bf16 v[90:93], v[144:147], v[212:215], v[90:93]
	v_mfma_f32_16x16x32_bf16 v[78:81], v[136:139], v[220:223], v[78:81]
	v_mfma_f32_16x16x32_bf16 v[74:77], v[144:147], v[220:223], v[74:77]
	v_mfma_f32_16x16x32_bf16 v[132:135], v[140:143], v[196:199], v[132:135]
	v_mfma_f32_16x16x32_bf16 v[128:131], v[148:151], v[196:199], v[128:131]
	v_mfma_f32_16x16x32_bf16 v[116:119], v[140:143], v[208:211], v[114:117]
	v_mfma_f32_16x16x32_bf16 v[106:109], v[148:151], v[208:211], v[106:109]
	v_mfma_f32_16x16x32_bf16 v[94:97], v[140:143], v[216:219], v[94:97]
	v_mfma_f32_16x16x32_bf16 v[90:93], v[148:151], v[216:219], v[90:93]
	v_mfma_f32_16x16x32_bf16 v[78:81], v[140:143], v[224:227], v[78:81]
	v_mfma_f32_16x16x32_bf16 v[74:77], v[148:151], v[224:227], v[74:77]
	v_mfma_f32_16x16x32_bf16 v[124:127], v[152:155], v[192:195], v[124:127]
	v_mfma_f32_16x16x32_bf16 v[120:123], v[160:163], v[192:195], v[120:123]
	v_mfma_f32_16x16x32_bf16 v[102:105], v[152:155], v[200:203], v[102:105]
	v_mfma_f32_16x16x32_bf16 v[98:101], v[160:163], v[200:203], v[98:101]
	v_mfma_f32_16x16x32_bf16 v[86:89], v[152:155], v[212:215], v[86:89]
	v_mfma_f32_16x16x32_bf16 v[82:85], v[160:163], v[212:215], v[82:85]
	v_mfma_f32_16x16x32_bf16 v[70:73], v[152:155], v[220:223], v[70:73]
	v_mfma_f32_16x16x32_bf16 v[66:69], v[160:163], v[220:223], v[66:69]
	v_mfma_f32_16x16x32_bf16 v[124:127], v[156:159], v[196:199], v[124:127]
	v_mfma_f32_16x16x32_bf16 v[120:123], v[164:167], v[196:199], v[120:123]
	v_mfma_f32_16x16x32_bf16 v[102:105], v[156:159], v[208:211], v[102:105]
	v_mfma_f32_16x16x32_bf16 v[98:101], v[164:167], v[208:211], v[98:101]
	v_mfma_f32_16x16x32_bf16 v[86:89], v[156:159], v[216:219], v[86:89]
	v_mfma_f32_16x16x32_bf16 v[82:85], v[164:167], v[216:219], v[82:85]
	v_mfma_f32_16x16x32_bf16 v[70:73], v[156:159], v[224:227], v[70:73]
	v_mfma_f32_16x16x32_bf16 v[66:69], v[164:167], v[224:227], v[66:69]
	s_setprio 0
	s_barrier
	s_add_i32 s6, s58, s27
	v_lshl_add_u64 v[114:115], v[204:205], 0, s[38:39]
	s_mov_b32 m0, s6
	ds_read_b128 v[192:195], v190 offset:49152
	ds_read_b128 v[196:199], v190 offset:50176
	ds_read_b128 v[200:203], v190 offset:51200
	ds_read_b128 v[208:211], v190 offset:52224
	ds_read_b128 v[212:215], v190 offset:53248
	ds_read_b128 v[216:219], v190 offset:54272
	ds_read_b128 v[220:223], v190 offset:55296
	ds_read_b128 v[224:227], v190 offset:56320
	global_load_lds_dwordx4 v[114:115], off
	v_lshl_add_u64 v[114:115], v[228:229], 0, s[38:39]
	s_add_i32 m0, s6, 0x2000
	s_add_i32 s6, s59, s27
	global_load_lds_dwordx4 v[114:115], off
	v_lshl_add_u64 v[114:115], v[230:231], 0, s[38:39]
	s_mov_b32 m0, s6
	s_nop 0
	global_load_lds_dwordx4 v[114:115], off
	v_lshl_add_u64 v[114:115], v[232:233], 0, s[38:39]
	s_add_i32 m0, s6, 0x2000
	s_nop 0
	global_load_lds_dwordx4 v[114:115], off
	v_lshl_add_u64 v[114:115], v[234:235], 0, s[38:39]
	s_mov_b32 m0, s45
	s_nop 0
	global_load_lds_dwordx4 v[114:115], off
	v_lshl_add_u64 v[114:115], v[236:237], 0, s[38:39]
	s_mov_b32 m0, s60
	s_nop 0
	global_load_lds_dwordx4 v[114:115], off
	s_waitcnt vmcnt(8)
	s_waitcnt lgkmcnt(0)
	s_barrier
	s_setprio 1
	s_waitcnt lgkmcnt(0)
	v_mfma_f32_16x16x32_bf16 v[62:65], v[136:139], v[192:195], v[62:65]
	v_mfma_f32_16x16x32_bf16 v[58:61], v[144:147], v[192:195], v[58:61]
	v_mfma_f32_16x16x32_bf16 v[46:49], v[136:139], v[200:203], v[46:49]
	v_mfma_f32_16x16x32_bf16 v[42:45], v[144:147], v[200:203], v[42:45]
	v_mfma_f32_16x16x32_bf16 v[30:33], v[136:139], v[212:215], v[30:33]
	v_mfma_f32_16x16x32_bf16 v[26:29], v[144:147], v[212:215], v[26:29]
	v_mfma_f32_16x16x32_bf16 v[14:17], v[136:139], v[220:223], v[14:17]
	v_mfma_f32_16x16x32_bf16 v[10:13], v[144:147], v[220:223], v[10:13]
	v_mfma_f32_16x16x32_bf16 v[62:65], v[140:143], v[196:199], v[62:65]
	v_mfma_f32_16x16x32_bf16 v[58:61], v[148:151], v[196:199], v[58:61]
	v_mfma_f32_16x16x32_bf16 v[46:49], v[140:143], v[208:211], v[46:49]
	v_mfma_f32_16x16x32_bf16 v[42:45], v[148:151], v[208:211], v[42:45]
	v_mfma_f32_16x16x32_bf16 v[30:33], v[140:143], v[216:219], v[30:33]
	v_mfma_f32_16x16x32_bf16 v[26:29], v[148:151], v[216:219], v[26:29]
	v_mfma_f32_16x16x32_bf16 v[14:17], v[140:143], v[224:227], v[14:17]
	v_mfma_f32_16x16x32_bf16 v[10:13], v[148:151], v[224:227], v[10:13]
	v_mfma_f32_16x16x32_bf16 v[54:57], v[152:155], v[192:195], v[54:57]
	v_mfma_f32_16x16x32_bf16 v[50:53], v[160:163], v[192:195], v[50:53]
	v_mfma_f32_16x16x32_bf16 v[38:41], v[152:155], v[200:203], v[38:41]
	v_mfma_f32_16x16x32_bf16 v[34:37], v[160:163], v[200:203], v[34:37]
	v_mfma_f32_16x16x32_bf16 v[22:25], v[152:155], v[212:215], v[22:25]
	v_mfma_f32_16x16x32_bf16 v[18:21], v[160:163], v[212:215], v[18:21]
	v_mfma_f32_16x16x32_bf16 v[6:9], v[152:155], v[220:223], v[6:9]
	v_mfma_f32_16x16x32_bf16 v[2:5], v[160:163], v[220:223], v[2:5]
	v_mfma_f32_16x16x32_bf16 v[54:57], v[156:159], v[196:199], v[54:57]
	v_mfma_f32_16x16x32_bf16 v[50:53], v[164:167], v[196:199], v[50:53]
	v_mfma_f32_16x16x32_bf16 v[38:41], v[156:159], v[208:211], v[38:41]
	v_mfma_f32_16x16x32_bf16 v[34:37], v[164:167], v[208:211], v[34:37]
	v_mfma_f32_16x16x32_bf16 v[22:25], v[156:159], v[216:219], v[22:25]
	v_mfma_f32_16x16x32_bf16 v[18:21], v[164:167], v[216:219], v[18:21]
	v_mfma_f32_16x16x32_bf16 v[6:9], v[156:159], v[224:227], v[6:9]
	v_mfma_f32_16x16x32_bf16 v[2:5], v[164:167], v[224:227], v[2:5]
	s_setprio 0
	s_barrier
	s_add_u32 s4, s4, 0x100
	s_addc_u32 s5, s5, 0
	s_add_u32 s31, s31, 0x100
	s_addc_u32 s36, s36, 0
	s_cmp_ge_i32 s37, s61
	s_mov_b32 s6, s37
	s_cbranch_scc0 .LBB0_253

.LBB0_529:
	ds_read_b128 v[128:131], v210
	ds_read_b128 v[132:135], v210 offset:1024
	ds_read_b128 v[136:139], v210 offset:2048
	ds_read_b128 v[140:143], v210 offset:3072
	ds_read_b128 v[144:147], v211
	ds_read_b128 v[148:151], v211 offset:1024
	ds_read_b128 v[152:155], v211 offset:2048
	ds_read_b128 v[156:159], v211 offset:3072
	s_add_i32 s65, s54, 2
	s_add_u32 s66, s52, 0x80
	s_addc_u32 s55, s53, 0
	s_cmp_eq_u32 s59, s54
	s_cselect_b32 s54, s10, s66
	s_cselect_b32 s55, s11, s55
	s_cselect_b32 s67, s51, s64
	s_cselect_b32 s66, s50, s16
	v_lshl_add_u64 v[218:219], s[52:53], 0, v[186:187]
	s_add_i32 m0, s25, 0xc000
	ds_read_b128 v[160:163], v212
	ds_read_b128 v[164:167], v212 offset:1024
	ds_read_b128 v[168:171], v212 offset:2048
	ds_read_b128 v[172:175], v212 offset:3072
	ds_read_b128 v[194:197], v212 offset:4096
	ds_read_b128 v[198:201], v212 offset:5120
	ds_read_b128 v[202:205], v212 offset:6144
	ds_read_b128 v[214:217], v212 offset:7168
	global_load_lds_dwordx4 v[218:219], off
	v_lshl_add_u64 v[218:219], s[52:53], 0, v[188:189]
	s_add_i32 m0, s25, 0xe000
	s_nop 0
	global_load_lds_dwordx4 v[218:219], off
	s_waitcnt vmcnt(8)
	s_waitcnt lgkmcnt(0)
	s_barrier
	s_setprio 1
	s_waitcnt lgkmcnt(0)
	v_mfma_f32_16x16x32_bf16 v[120:123], v[128:131], v[160:163], v[120:123]
	v_mfma_f32_16x16x32_bf16 v[124:127], v[136:139], v[160:163], v[124:127]
	v_mfma_f32_16x16x32_bf16 v[108:111], v[128:131], v[168:171], v[108:111]
	v_mfma_f32_16x16x32_bf16 v[104:107], v[136:139], v[168:171], v[104:107]
	v_mfma_f32_16x16x32_bf16 v[92:95], v[128:131], v[194:197], v[92:95]
	v_mfma_f32_16x16x32_bf16 v[88:91], v[136:139], v[194:197], v[88:91]
	v_mfma_f32_16x16x32_bf16 v[76:79], v[128:131], v[202:205], v[76:79]
	v_mfma_f32_16x16x32_bf16 v[72:75], v[136:139], v[202:205], v[72:75]
	v_mfma_f32_16x16x32_bf16 v[120:123], v[132:135], v[164:167], v[120:123]
	v_mfma_f32_16x16x32_bf16 v[124:127], v[140:143], v[164:167], v[124:127]
	v_mfma_f32_16x16x32_bf16 v[108:111], v[132:135], v[172:175], v[108:111]
	v_mfma_f32_16x16x32_bf16 v[104:107], v[140:143], v[172:175], v[104:107]
	v_mfma_f32_16x16x32_bf16 v[92:95], v[132:135], v[198:201], v[92:95]
	v_mfma_f32_16x16x32_bf16 v[88:91], v[140:143], v[198:201], v[88:91]
	v_mfma_f32_16x16x32_bf16 v[76:79], v[132:135], v[214:217], v[76:79]
	v_mfma_f32_16x16x32_bf16 v[72:75], v[140:143], v[214:217], v[72:75]
	v_mfma_f32_16x16x32_bf16 v[116:119], v[144:147], v[160:163], v[116:119]
	v_mfma_f32_16x16x32_bf16 v[112:115], v[152:155], v[160:163], v[112:115]
	v_mfma_f32_16x16x32_bf16 v[100:103], v[144:147], v[168:171], v[100:103]
	v_mfma_f32_16x16x32_bf16 v[96:99], v[152:155], v[168:171], v[96:99]
	v_mfma_f32_16x16x32_bf16 v[84:87], v[144:147], v[194:197], v[84:87]
	v_mfma_f32_16x16x32_bf16 v[80:83], v[152:155], v[194:197], v[80:83]
	v_mfma_f32_16x16x32_bf16 v[68:71], v[144:147], v[202:205], v[68:71]
	v_mfma_f32_16x16x32_bf16 v[64:67], v[152:155], v[202:205], v[64:67]
	v_mfma_f32_16x16x32_bf16 v[116:119], v[148:151], v[164:167], v[116:119]
	v_mfma_f32_16x16x32_bf16 v[112:115], v[156:159], v[164:167], v[112:115]
	v_mfma_f32_16x16x32_bf16 v[100:103], v[148:151], v[172:175], v[100:103]
	v_mfma_f32_16x16x32_bf16 v[96:99], v[156:159], v[172:175], v[96:99]
	v_mfma_f32_16x16x32_bf16 v[84:87], v[148:151], v[198:201], v[84:87]
	v_mfma_f32_16x16x32_bf16 v[80:83], v[156:159], v[198:201], v[80:83]
	v_mfma_f32_16x16x32_bf16 v[68:71], v[148:151], v[214:217], v[68:71]
	v_mfma_f32_16x16x32_bf16 v[64:67], v[156:159], v[214:217], v[64:67]
	s_setprio 0
	s_barrier
	s_add_i32 s68, s60, s24
	v_lshl_add_u64 v[218:219], s[66:67], 0, v[178:179]
	s_mov_b32 m0, s68
	ds_read_b128 v[160:163], v212 offset:16384
	ds_read_b128 v[164:167], v212 offset:17408
	ds_read_b128 v[168:171], v212 offset:18432
	ds_read_b128 v[172:175], v212 offset:19456
	ds_read_b128 v[194:197], v212 offset:20480
	ds_read_b128 v[198:201], v212 offset:21504
	ds_read_b128 v[202:205], v212 offset:22528
	ds_read_b128 v[214:217], v212 offset:23552
	global_load_lds_dwordx4 v[218:219], off
	s_add_i32 m0, s68, 0x2000
	v_lshl_add_u64 v[220:221], s[66:67], 0, v[182:183]
	s_add_u32 s66, s66, s28
	s_addc_u32 s67, s67, s29
	s_add_i32 s68, s61, s24
	global_load_lds_dwordx4 v[220:221], off
	v_lshl_add_u64 v[222:223], s[66:67], 0, v[178:179]
	s_mov_b32 m0, s68
	v_lshl_add_u64 v[224:225], s[66:67], 0, v[182:183]
	global_load_lds_dwordx4 v[222:223], off
	s_add_i32 m0, s68, 0x2000
	v_lshl_add_u64 v[226:227], s[54:55], 0, v[176:177]
	global_load_lds_dwordx4 v[224:225], off
	s_mov_b32 m0, s25
	v_lshl_add_u64 v[228:229], s[54:55], 0, v[180:181]
	global_load_lds_dwordx4 v[226:227], off
	s_mov_b32 m0, s26
	s_nop 0
	global_load_lds_dwordx4 v[228:229], off
	s_waitcnt vmcnt(8)
	s_waitcnt lgkmcnt(0)
	s_barrier
	s_setprio 1
	s_waitcnt lgkmcnt(0)
	v_mfma_f32_16x16x32_bf16 v[60:63], v[128:131], v[160:163], v[60:63]
	v_mfma_f32_16x16x32_bf16 v[56:59], v[136:139], v[160:163], v[56:59]
	v_mfma_f32_16x16x32_bf16 v[44:47], v[128:131], v[168:171], v[44:47]
	v_mfma_f32_16x16x32_bf16 v[40:43], v[136:139], v[168:171], v[40:43]
	v_mfma_f32_16x16x32_bf16 v[28:31], v[128:131], v[194:197], v[28:31]
	v_mfma_f32_16x16x32_bf16 v[24:27], v[136:139], v[194:197], v[24:27]
	v_mfma_f32_16x16x32_bf16 v[12:15], v[128:131], v[202:205], v[12:15]
	v_mfma_f32_16x16x32_bf16 v[8:11], v[136:139], v[202:205], v[8:11]
	v_mfma_f32_16x16x32_bf16 v[60:63], v[132:135], v[164:167], v[60:63]
	v_mfma_f32_16x16x32_bf16 v[56:59], v[140:143], v[164:167], v[56:59]
	v_mfma_f32_16x16x32_bf16 v[44:47], v[132:135], v[172:175], v[44:47]
	v_mfma_f32_16x16x32_bf16 v[40:43], v[140:143], v[172:175], v[40:43]
	v_mfma_f32_16x16x32_bf16 v[28:31], v[132:135], v[198:201], v[28:31]
	v_mfma_f32_16x16x32_bf16 v[24:27], v[140:143], v[198:201], v[24:27]
	v_mfma_f32_16x16x32_bf16 v[12:15], v[132:135], v[214:217], v[12:15]
	v_mfma_f32_16x16x32_bf16 v[8:11], v[140:143], v[214:217], v[8:11]
	v_mfma_f32_16x16x32_bf16 v[52:55], v[144:147], v[160:163], v[52:55]
	v_mfma_f32_16x16x32_bf16 v[48:51], v[152:155], v[160:163], v[48:51]
	v_mfma_f32_16x16x32_bf16 v[36:39], v[144:147], v[168:171], v[36:39]
	v_mfma_f32_16x16x32_bf16 v[32:35], v[152:155], v[168:171], v[32:35]
	v_mfma_f32_16x16x32_bf16 v[20:23], v[144:147], v[194:197], v[20:23]
	v_mfma_f32_16x16x32_bf16 v[16:19], v[152:155], v[194:197], v[16:19]
	v_mfma_f32_16x16x32_bf16 v[4:7], v[144:147], v[202:205], v[4:7]
	v_mfma_f32_16x16x32_bf16 v[0:3], v[152:155], v[202:205], v[0:3]
	v_mfma_f32_16x16x32_bf16 v[52:55], v[148:151], v[164:167], v[52:55]
	v_mfma_f32_16x16x32_bf16 v[48:51], v[156:159], v[164:167], v[48:51]
	v_mfma_f32_16x16x32_bf16 v[36:39], v[148:151], v[172:175], v[36:39]
	v_mfma_f32_16x16x32_bf16 v[32:35], v[156:159], v[172:175], v[32:35]
	v_mfma_f32_16x16x32_bf16 v[20:23], v[148:151], v[198:201], v[20:23]
	v_mfma_f32_16x16x32_bf16 v[16:19], v[156:159], v[198:201], v[16:19]
	v_mfma_f32_16x16x32_bf16 v[4:7], v[148:151], v[214:217], v[4:7]
	v_mfma_f32_16x16x32_bf16 v[0:3], v[156:159], v[214:217], v[0:3]
	s_setprio 0
	s_barrier
	s_add_i32 s66, 0, 0x18000
	s_add_i32 s67, 0, 0x1c000
	v_add_u32_e32 v140, s66, v208
	v_add_u32_e32 v156, s67, v208
	ds_read_b128 v[128:131], v140
	ds_read_b128 v[132:135], v140 offset:1024
	ds_read_b128 v[136:139], v140 offset:2048
	ds_read_b128 v[140:143], v140 offset:3072
	ds_read_b128 v[144:147], v156
	ds_read_b128 v[148:151], v156 offset:1024
	ds_read_b128 v[152:155], v156 offset:2048
	ds_read_b128 v[156:159], v156 offset:3072
	s_add_u32 s54, s54, s28
	s_addc_u32 s55, s55, s29
	s_mov_b32 m0, s27
	v_lshl_add_u64 v[230:231], s[54:55], 0, v[176:177]
	ds_read_b128 v[160:163], v212 offset:32768
	ds_read_b128 v[164:167], v212 offset:33792
	ds_read_b128 v[168:171], v212 offset:34816
	ds_read_b128 v[172:175], v212 offset:35840
	ds_read_b128 v[194:197], v212 offset:36864
	ds_read_b128 v[198:201], v212 offset:37888
	ds_read_b128 v[202:205], v212 offset:38912
	ds_read_b128 v[214:217], v212 offset:39936
	global_load_lds_dwordx4 v[230:231], off
	v_lshl_add_u64 v[230:231], s[54:55], 0, v[180:181]
	s_mov_b32 m0, s44
	s_nop 0
	global_load_lds_dwordx4 v[230:231], off
	s_waitcnt vmcnt(8)
	s_waitcnt lgkmcnt(0)
	s_barrier
	s_setprio 1
	s_waitcnt lgkmcnt(0)
	v_mfma_f32_16x16x32_bf16 v[120:123], v[128:131], v[160:163], v[120:123]
	v_mfma_f32_16x16x32_bf16 v[124:127], v[136:139], v[160:163], v[124:127]
	v_mfma_f32_16x16x32_bf16 v[108:111], v[128:131], v[168:171], v[108:111]
	v_mfma_f32_16x16x32_bf16 v[104:107], v[136:139], v[168:171], v[104:107]
	v_mfma_f32_16x16x32_bf16 v[92:95], v[128:131], v[194:197], v[92:95]
	v_mfma_f32_16x16x32_bf16 v[88:91], v[136:139], v[194:197], v[88:91]
	v_mfma_f32_16x16x32_bf16 v[76:79], v[128:131], v[202:205], v[76:79]
	v_mfma_f32_16x16x32_bf16 v[72:75], v[136:139], v[202:205], v[72:75]
	v_mfma_f32_16x16x32_bf16 v[120:123], v[132:135], v[164:167], v[120:123]
	v_mfma_f32_16x16x32_bf16 v[124:127], v[140:143], v[164:167], v[124:127]
	v_mfma_f32_16x16x32_bf16 v[108:111], v[132:135], v[172:175], v[108:111]
	v_mfma_f32_16x16x32_bf16 v[104:107], v[140:143], v[172:175], v[104:107]
	v_mfma_f32_16x16x32_bf16 v[92:95], v[132:135], v[198:201], v[92:95]
	v_mfma_f32_16x16x32_bf16 v[88:91], v[140:143], v[198:201], v[88:91]
	v_mfma_f32_16x16x32_bf16 v[76:79], v[132:135], v[214:217], v[76:79]
	v_mfma_f32_16x16x32_bf16 v[72:75], v[140:143], v[214:217], v[72:75]
	v_mfma_f32_16x16x32_bf16 v[116:119], v[144:147], v[160:163], v[116:119]
	v_mfma_f32_16x16x32_bf16 v[112:115], v[152:155], v[160:163], v[112:115]
	v_mfma_f32_16x16x32_bf16 v[100:103], v[144:147], v[168:171], v[100:103]
	v_mfma_f32_16x16x32_bf16 v[96:99], v[152:155], v[168:171], v[96:99]
	v_mfma_f32_16x16x32_bf16 v[84:87], v[144:147], v[194:197], v[84:87]
	v_mfma_f32_16x16x32_bf16 v[80:83], v[152:155], v[194:197], v[80:83]
	v_mfma_f32_16x16x32_bf16 v[68:71], v[144:147], v[202:205], v[68:71]
	v_mfma_f32_16x16x32_bf16 v[64:67], v[152:155], v[202:205], v[64:67]
	v_mfma_f32_16x16x32_bf16 v[116:119], v[148:151], v[164:167], v[116:119]
	v_mfma_f32_16x16x32_bf16 v[112:115], v[156:159], v[164:167], v[112:115]
	v_mfma_f32_16x16x32_bf16 v[100:103], v[148:151], v[172:175], v[100:103]
	v_mfma_f32_16x16x32_bf16 v[96:99], v[156:159], v[172:175], v[96:99]
	v_mfma_f32_16x16x32_bf16 v[84:87], v[148:151], v[198:201], v[84:87]
	v_mfma_f32_16x16x32_bf16 v[80:83], v[156:159], v[198:201], v[80:83]
	v_mfma_f32_16x16x32_bf16 v[68:71], v[148:151], v[214:217], v[68:71]
	v_mfma_f32_16x16x32_bf16 v[64:67], v[156:159], v[214:217], v[64:67]
	s_setprio 0
	s_barrier
	s_add_i32 s54, s66, s24
	v_lshl_add_u64 v[218:219], v[218:219], 0, s[42:43]
	s_mov_b32 m0, s54
	ds_read_b128 v[160:163], v212 offset:49152
	ds_read_b128 v[164:167], v212 offset:50176
	ds_read_b128 v[168:171], v212 offset:51200
	ds_read_b128 v[172:175], v212 offset:52224
	ds_read_b128 v[194:197], v212 offset:53248
	ds_read_b128 v[198:201], v212 offset:54272
	ds_read_b128 v[202:205], v212 offset:55296
	ds_read_b128 v[214:217], v212 offset:56320
	global_load_lds_dwordx4 v[218:219], off
	v_lshl_add_u64 v[218:219], v[220:221], 0, s[42:43]
	s_add_i32 m0, s54, 0x2000
	s_add_i32 s54, s67, s24
	global_load_lds_dwordx4 v[218:219], off
	v_lshl_add_u64 v[218:219], v[222:223], 0, s[42:43]
	s_mov_b32 m0, s54
	s_nop 0
	global_load_lds_dwordx4 v[218:219], off
	v_lshl_add_u64 v[218:219], v[224:225], 0, s[42:43]
	s_add_i32 m0, s54, 0x2000
	s_nop 0
	global_load_lds_dwordx4 v[218:219], off
	v_lshl_add_u64 v[218:219], v[226:227], 0, s[42:43]
	s_mov_b32 m0, s56
	s_nop 0
	global_load_lds_dwordx4 v[218:219], off
	v_lshl_add_u64 v[218:219], v[228:229], 0, s[42:43]
	s_mov_b32 m0, s57
	s_nop 0
	global_load_lds_dwordx4 v[218:219], off
	s_waitcnt vmcnt(8)
	s_waitcnt lgkmcnt(0)
	s_barrier
	s_setprio 1
	s_waitcnt lgkmcnt(0)
	v_mfma_f32_16x16x32_bf16 v[60:63], v[128:131], v[160:163], v[60:63]
	v_mfma_f32_16x16x32_bf16 v[56:59], v[136:139], v[160:163], v[56:59]
	v_mfma_f32_16x16x32_bf16 v[44:47], v[128:131], v[168:171], v[44:47]
	v_mfma_f32_16x16x32_bf16 v[40:43], v[136:139], v[168:171], v[40:43]
	v_mfma_f32_16x16x32_bf16 v[28:31], v[128:131], v[194:197], v[28:31]
	v_mfma_f32_16x16x32_bf16 v[24:27], v[136:139], v[194:197], v[24:27]
	v_mfma_f32_16x16x32_bf16 v[12:15], v[128:131], v[202:205], v[12:15]
	v_mfma_f32_16x16x32_bf16 v[8:11], v[136:139], v[202:205], v[8:11]
	v_mfma_f32_16x16x32_bf16 v[60:63], v[132:135], v[164:167], v[60:63]
	v_mfma_f32_16x16x32_bf16 v[56:59], v[140:143], v[164:167], v[56:59]
	v_mfma_f32_16x16x32_bf16 v[44:47], v[132:135], v[172:175], v[44:47]
	v_mfma_f32_16x16x32_bf16 v[40:43], v[140:143], v[172:175], v[40:43]
	v_mfma_f32_16x16x32_bf16 v[28:31], v[132:135], v[198:201], v[28:31]
	v_mfma_f32_16x16x32_bf16 v[24:27], v[140:143], v[198:201], v[24:27]
	v_mfma_f32_16x16x32_bf16 v[12:15], v[132:135], v[214:217], v[12:15]
	v_mfma_f32_16x16x32_bf16 v[8:11], v[140:143], v[214:217], v[8:11]
	v_mfma_f32_16x16x32_bf16 v[52:55], v[144:147], v[160:163], v[52:55]
	v_mfma_f32_16x16x32_bf16 v[48:51], v[152:155], v[160:163], v[48:51]
	v_mfma_f32_16x16x32_bf16 v[36:39], v[144:147], v[168:171], v[36:39]
	v_mfma_f32_16x16x32_bf16 v[32:35], v[152:155], v[168:171], v[32:35]
	v_mfma_f32_16x16x32_bf16 v[20:23], v[144:147], v[194:197], v[20:23]
	v_mfma_f32_16x16x32_bf16 v[16:19], v[152:155], v[194:197], v[16:19]
	v_mfma_f32_16x16x32_bf16 v[4:7], v[144:147], v[202:205], v[4:7]
	v_mfma_f32_16x16x32_bf16 v[0:3], v[152:155], v[202:205], v[0:3]
	v_mfma_f32_16x16x32_bf16 v[52:55], v[148:151], v[164:167], v[52:55]
	v_mfma_f32_16x16x32_bf16 v[48:51], v[156:159], v[164:167], v[48:51]
	v_mfma_f32_16x16x32_bf16 v[36:39], v[148:151], v[172:175], v[36:39]
	v_mfma_f32_16x16x32_bf16 v[32:35], v[156:159], v[172:175], v[32:35]
	v_mfma_f32_16x16x32_bf16 v[20:23], v[148:151], v[198:201], v[20:23]
	v_mfma_f32_16x16x32_bf16 v[16:19], v[156:159], v[198:201], v[16:19]
	v_mfma_f32_16x16x32_bf16 v[4:7], v[148:151], v[214:217], v[4:7]
	v_mfma_f32_16x16x32_bf16 v[0:3], v[156:159], v[214:217], v[0:3]
	s_setprio 0
	s_barrier
	s_add_u32 s52, s52, 0x100
	s_addc_u32 s53, s53, 0
	s_add_u32 s16, s16, 0x100
	s_addc_u32 s64, s64, 0
	s_cmp_ge_i32 s65, s58
	s_mov_b32 s54, s65
	s_cbranch_scc0 .LBB0_529

.LBB0_624:
	s_add_i32 vcc_lo, s90, 2
	s_add_u32 s44, s88, 0x80
	s_addc_u32 s45, s89, 0
	s_add_i32 vcc_hi, 0, 0x10000
	s_cmp_eq_u32 s55, s90
	s_cselect_b32 s91, s11, s45
	s_cselect_b32 s90, s10, s44
	v_add_u32_e32 v128, vcc_hi, v147
	s_cselect_b32 s45, s87, s16
	s_cselect_b32 s44, s86, s15
	s_add_i32 s58, 0, 0x14000
	ds_read_b128 v[156:159], v128
	ds_read_b128 v[160:163], v128 offset:1024
	ds_read_b128 v[164:167], v128 offset:2048
	ds_read_b128 v[168:171], v128 offset:3072
	v_add_u32_e32 v128, s58, v147
	ds_read_b128 v[172:175], v128
	ds_read_b128 v[184:187], v128 offset:1024
	ds_read_b128 v[188:191], v128 offset:2048
	ds_read_b128 v[192:195], v128 offset:3072
	v_lshl_add_u64 v[176:177], s[88:89], 0, v[138:139]
	s_add_i32 m0, s93, 0xc000
	ds_read_b128 v[204:207], v155
	ds_read_b128 v[208:211], v155 offset:1024
	ds_read_b128 v[212:215], v155 offset:2048
	ds_read_b128 v[216:219], v155 offset:3072
	ds_read_b128 v[220:223], v155 offset:4096
	ds_read_b128 v[224:227], v155 offset:5120
	ds_read_b128 v[228:231], v155 offset:6144
	ds_read_b128 v[232:235], v155 offset:7168
	global_load_lds_dwordx4 v[176:177], off
	v_lshl_add_u64 v[176:177], s[88:89], 0, v[140:141]
	s_add_i32 m0, s93, 0xe000
	s_nop 0
	global_load_lds_dwordx4 v[176:177], off
	s_waitcnt vmcnt(8)
	s_waitcnt lgkmcnt(0)
	s_barrier
	s_setprio 1
	s_waitcnt lgkmcnt(0)
	v_mfma_f32_16x16x32_bf16 v[124:127], v[156:159], v[204:207], v[124:127]
	v_mfma_f32_16x16x32_bf16 v[120:123], v[164:167], v[204:207], v[120:123]
	v_mfma_f32_16x16x32_bf16 v[108:111], v[156:159], v[212:215], v[108:111]
	v_mfma_f32_16x16x32_bf16 v[104:107], v[164:167], v[212:215], v[104:107]
	v_mfma_f32_16x16x32_bf16 v[92:95], v[156:159], v[220:223], v[92:95]
	v_mfma_f32_16x16x32_bf16 v[88:91], v[164:167], v[220:223], v[88:91]
	v_mfma_f32_16x16x32_bf16 v[76:79], v[156:159], v[228:231], v[76:79]
	v_mfma_f32_16x16x32_bf16 v[72:75], v[164:167], v[228:231], v[72:75]
	v_mfma_f32_16x16x32_bf16 v[124:127], v[160:163], v[208:211], v[124:127]
	v_mfma_f32_16x16x32_bf16 v[120:123], v[168:171], v[208:211], v[120:123]
	v_mfma_f32_16x16x32_bf16 v[108:111], v[160:163], v[216:219], v[108:111]
	v_mfma_f32_16x16x32_bf16 v[104:107], v[168:171], v[216:219], v[104:107]
	v_mfma_f32_16x16x32_bf16 v[92:95], v[160:163], v[224:227], v[92:95]
	v_mfma_f32_16x16x32_bf16 v[88:91], v[168:171], v[224:227], v[88:91]
	v_mfma_f32_16x16x32_bf16 v[76:79], v[160:163], v[232:235], v[76:79]
	v_mfma_f32_16x16x32_bf16 v[72:75], v[168:171], v[232:235], v[72:75]
	v_mfma_f32_16x16x32_bf16 v[116:119], v[172:175], v[204:207], v[116:119]
	v_mfma_f32_16x16x32_bf16 v[112:115], v[188:191], v[204:207], v[112:115]
	v_mfma_f32_16x16x32_bf16 v[100:103], v[172:175], v[212:215], v[100:103]
	v_mfma_f32_16x16x32_bf16 v[96:99], v[188:191], v[212:215], v[96:99]
	v_mfma_f32_16x16x32_bf16 v[84:87], v[172:175], v[220:223], v[84:87]
	v_mfma_f32_16x16x32_bf16 v[80:83], v[188:191], v[220:223], v[80:83]
	v_mfma_f32_16x16x32_bf16 v[68:71], v[172:175], v[228:231], v[68:71]
	v_mfma_f32_16x16x32_bf16 v[64:67], v[188:191], v[228:231], v[64:67]
	v_mfma_f32_16x16x32_bf16 v[116:119], v[184:187], v[208:211], v[116:119]
	v_mfma_f32_16x16x32_bf16 v[112:115], v[192:195], v[208:211], v[112:115]
	v_mfma_f32_16x16x32_bf16 v[100:103], v[184:187], v[216:219], v[100:103]
	v_mfma_f32_16x16x32_bf16 v[96:99], v[192:195], v[216:219], v[96:99]
	v_mfma_f32_16x16x32_bf16 v[84:87], v[184:187], v[224:227], v[84:87]
	v_mfma_f32_16x16x32_bf16 v[80:83], v[192:195], v[224:227], v[80:83]
	v_mfma_f32_16x16x32_bf16 v[68:71], v[184:187], v[232:235], v[68:71]
	v_mfma_f32_16x16x32_bf16 v[64:67], v[192:195], v[232:235], v[64:67]
	s_setprio 0
	s_barrier
	s_add_i32 vcc_hi, vcc_hi, s92
	v_lshl_add_u64 v[176:177], s[44:45], 0, v[134:135]
	s_mov_b32 m0, vcc_hi
	ds_read_b128 v[204:207], v155 offset:16384
	ds_read_b128 v[208:211], v155 offset:17408
	ds_read_b128 v[212:215], v155 offset:18432
	ds_read_b128 v[216:219], v155 offset:19456
	ds_read_b128 v[220:223], v155 offset:20480
	ds_read_b128 v[224:227], v155 offset:21504
	ds_read_b128 v[228:231], v155 offset:22528
	ds_read_b128 v[232:235], v155 offset:23552
	global_load_lds_dwordx4 v[176:177], off
	s_add_i32 m0, vcc_hi, 0x2000
	v_lshl_add_u64 v[178:179], s[44:45], 0, v[130:131]
	s_add_u32 s44, s44, s66
	s_addc_u32 s45, s45, s67
	s_add_i32 s58, s58, s92
	global_load_lds_dwordx4 v[178:179], off
	v_lshl_add_u64 v[180:181], s[44:45], 0, v[134:135]
	s_mov_b32 m0, s58
	v_lshl_add_u64 v[236:237], s[44:45], 0, v[130:131]
	global_load_lds_dwordx4 v[180:181], off
	s_add_i32 m0, s58, 0x2000
	v_lshl_add_u64 v[238:239], s[90:91], 0, v[136:137]
	global_load_lds_dwordx4 v[236:237], off
	s_mov_b32 m0, s93
	v_lshl_add_u64 v[240:241], s[90:91], 0, v[132:133]
	global_load_lds_dwordx4 v[238:239], off
	s_mov_b32 m0, s94
	s_nop 0
	global_load_lds_dwordx4 v[240:241], off
	s_waitcnt vmcnt(8)
	s_waitcnt lgkmcnt(0)
	s_barrier
	s_setprio 1
	s_waitcnt lgkmcnt(0)
	v_mfma_f32_16x16x32_bf16 v[60:63], v[156:159], v[204:207], v[60:63]
	v_mfma_f32_16x16x32_bf16 v[56:59], v[164:167], v[204:207], v[56:59]
	v_mfma_f32_16x16x32_bf16 v[44:47], v[156:159], v[212:215], v[44:47]
	v_mfma_f32_16x16x32_bf16 v[40:43], v[164:167], v[212:215], v[40:43]
	v_mfma_f32_16x16x32_bf16 v[28:31], v[156:159], v[220:223], v[28:31]
	v_mfma_f32_16x16x32_bf16 v[24:27], v[164:167], v[220:223], v[24:27]
	v_mfma_f32_16x16x32_bf16 v[12:15], v[156:159], v[228:231], v[12:15]
	v_mfma_f32_16x16x32_bf16 v[8:11], v[164:167], v[228:231], v[8:11]
	v_mfma_f32_16x16x32_bf16 v[60:63], v[160:163], v[208:211], v[60:63]
	v_mfma_f32_16x16x32_bf16 v[56:59], v[168:171], v[208:211], v[56:59]
	v_mfma_f32_16x16x32_bf16 v[44:47], v[160:163], v[216:219], v[44:47]
	v_mfma_f32_16x16x32_bf16 v[40:43], v[168:171], v[216:219], v[40:43]
	v_mfma_f32_16x16x32_bf16 v[28:31], v[160:163], v[224:227], v[28:31]
	v_mfma_f32_16x16x32_bf16 v[24:27], v[168:171], v[224:227], v[24:27]
	v_mfma_f32_16x16x32_bf16 v[12:15], v[160:163], v[232:235], v[12:15]
	v_mfma_f32_16x16x32_bf16 v[8:11], v[168:171], v[232:235], v[8:11]
	v_mfma_f32_16x16x32_bf16 v[52:55], v[172:175], v[204:207], v[52:55]
	v_mfma_f32_16x16x32_bf16 v[48:51], v[188:191], v[204:207], v[48:51]
	v_mfma_f32_16x16x32_bf16 v[36:39], v[172:175], v[212:215], v[36:39]
	v_mfma_f32_16x16x32_bf16 v[32:35], v[188:191], v[212:215], v[32:35]
	v_mfma_f32_16x16x32_bf16 v[20:23], v[172:175], v[220:223], v[20:23]
	v_mfma_f32_16x16x32_bf16 v[16:19], v[188:191], v[220:223], v[16:19]
	v_mfma_f32_16x16x32_bf16 v[4:7], v[172:175], v[228:231], v[4:7]
	v_mfma_f32_16x16x32_bf16 v[0:3], v[188:191], v[228:231], v[0:3]
	v_mfma_f32_16x16x32_bf16 v[52:55], v[184:187], v[208:211], v[52:55]
	v_mfma_f32_16x16x32_bf16 v[48:51], v[192:195], v[208:211], v[48:51]
	v_mfma_f32_16x16x32_bf16 v[36:39], v[184:187], v[216:219], v[36:39]
	v_mfma_f32_16x16x32_bf16 v[32:35], v[192:195], v[216:219], v[32:35]
	v_mfma_f32_16x16x32_bf16 v[20:23], v[184:187], v[224:227], v[20:23]
	v_mfma_f32_16x16x32_bf16 v[16:19], v[192:195], v[224:227], v[16:19]
	v_mfma_f32_16x16x32_bf16 v[4:7], v[184:187], v[232:235], v[4:7]
	v_mfma_f32_16x16x32_bf16 v[0:3], v[192:195], v[232:235], v[0:3]
	s_setprio 0
	s_barrier
	s_add_i32 s58, 0, 0x18000
	v_add_u32_e32 v128, s58, v147
	s_add_i32 vcc_hi, 0, 0x1c000
	ds_read_b128 v[156:159], v128
	ds_read_b128 v[160:163], v128 offset:1024
	ds_read_b128 v[164:167], v128 offset:2048
	ds_read_b128 v[168:171], v128 offset:3072
	v_add_u32_e32 v128, vcc_hi, v147
	ds_read_b128 v[172:175], v128
	ds_read_b128 v[184:187], v128 offset:1024
	ds_read_b128 v[188:191], v128 offset:2048
	ds_read_b128 v[192:195], v128 offset:3072
	s_add_u32 s44, s90, s66
	s_addc_u32 s45, s91, s67
	s_mov_b32 m0, s95
	v_lshl_add_u64 v[242:243], s[44:45], 0, v[136:137]
	ds_read_b128 v[204:207], v155 offset:32768
	ds_read_b128 v[208:211], v155 offset:33792
	ds_read_b128 v[212:215], v155 offset:34816
	ds_read_b128 v[216:219], v155 offset:35840
	ds_read_b128 v[220:223], v155 offset:36864
	ds_read_b128 v[224:227], v155 offset:37888
	ds_read_b128 v[228:231], v155 offset:38912
	ds_read_b128 v[232:235], v155 offset:39936
	global_load_lds_dwordx4 v[242:243], off
	v_lshl_add_u64 v[242:243], s[44:45], 0, v[132:133]
	s_mov_b32 m0, s96
	s_nop 0
	global_load_lds_dwordx4 v[242:243], off
	s_waitcnt vmcnt(8)
	s_waitcnt lgkmcnt(0)
	s_barrier
	s_setprio 1
	s_waitcnt lgkmcnt(0)
	v_mfma_f32_16x16x32_bf16 v[124:127], v[156:159], v[204:207], v[124:127]
	v_mfma_f32_16x16x32_bf16 v[120:123], v[164:167], v[204:207], v[120:123]
	v_mfma_f32_16x16x32_bf16 v[108:111], v[156:159], v[212:215], v[108:111]
	v_mfma_f32_16x16x32_bf16 v[104:107], v[164:167], v[212:215], v[104:107]
	v_mfma_f32_16x16x32_bf16 v[92:95], v[156:159], v[220:223], v[92:95]
	v_mfma_f32_16x16x32_bf16 v[88:91], v[164:167], v[220:223], v[88:91]
	v_mfma_f32_16x16x32_bf16 v[76:79], v[156:159], v[228:231], v[76:79]
	v_mfma_f32_16x16x32_bf16 v[72:75], v[164:167], v[228:231], v[72:75]
	v_mfma_f32_16x16x32_bf16 v[124:127], v[160:163], v[208:211], v[124:127]
	v_mfma_f32_16x16x32_bf16 v[120:123], v[168:171], v[208:211], v[120:123]
	v_mfma_f32_16x16x32_bf16 v[108:111], v[160:163], v[216:219], v[108:111]
	v_mfma_f32_16x16x32_bf16 v[104:107], v[168:171], v[216:219], v[104:107]
	v_mfma_f32_16x16x32_bf16 v[92:95], v[160:163], v[224:227], v[92:95]
	v_mfma_f32_16x16x32_bf16 v[88:91], v[168:171], v[224:227], v[88:91]
	v_mfma_f32_16x16x32_bf16 v[76:79], v[160:163], v[232:235], v[76:79]
	v_mfma_f32_16x16x32_bf16 v[72:75], v[168:171], v[232:235], v[72:75]
	v_mfma_f32_16x16x32_bf16 v[116:119], v[172:175], v[204:207], v[116:119]
	v_mfma_f32_16x16x32_bf16 v[112:115], v[188:191], v[204:207], v[112:115]
	v_mfma_f32_16x16x32_bf16 v[100:103], v[172:175], v[212:215], v[100:103]
	v_mfma_f32_16x16x32_bf16 v[96:99], v[188:191], v[212:215], v[96:99]
	v_mfma_f32_16x16x32_bf16 v[84:87], v[172:175], v[220:223], v[84:87]
	v_mfma_f32_16x16x32_bf16 v[80:83], v[188:191], v[220:223], v[80:83]
	v_mfma_f32_16x16x32_bf16 v[68:71], v[172:175], v[228:231], v[68:71]
	v_mfma_f32_16x16x32_bf16 v[64:67], v[188:191], v[228:231], v[64:67]
	v_mfma_f32_16x16x32_bf16 v[116:119], v[184:187], v[208:211], v[116:119]
	v_mfma_f32_16x16x32_bf16 v[112:115], v[192:195], v[208:211], v[112:115]
	v_mfma_f32_16x16x32_bf16 v[100:103], v[184:187], v[216:219], v[100:103]
	v_mfma_f32_16x16x32_bf16 v[96:99], v[192:195], v[216:219], v[96:99]
	v_mfma_f32_16x16x32_bf16 v[84:87], v[184:187], v[224:227], v[84:87]
	v_mfma_f32_16x16x32_bf16 v[80:83], v[192:195], v[224:227], v[80:83]
	v_mfma_f32_16x16x32_bf16 v[68:71], v[184:187], v[232:235], v[68:71]
	v_mfma_f32_16x16x32_bf16 v[64:67], v[192:195], v[232:235], v[64:67]
	s_setprio 0
	s_barrier
	s_add_i32 s44, s58, s92
	v_lshl_add_u64 v[176:177], v[176:177], 0, s[52:53]
	s_mov_b32 m0, s44
	ds_read_b128 v[204:207], v155 offset:49152
	ds_read_b128 v[208:211], v155 offset:50176
	ds_read_b128 v[212:215], v155 offset:51200
	ds_read_b128 v[216:219], v155 offset:52224
	ds_read_b128 v[220:223], v155 offset:53248
	ds_read_b128 v[224:227], v155 offset:54272
	ds_read_b128 v[228:231], v155 offset:55296
	ds_read_b128 v[232:235], v155 offset:56320
	global_load_lds_dwordx4 v[176:177], off
	v_lshl_add_u64 v[176:177], v[178:179], 0, s[52:53]
	s_add_i32 m0, s44, 0x2000
	s_add_i32 s44, vcc_hi, s92
	global_load_lds_dwordx4 v[176:177], off
	v_lshl_add_u64 v[176:177], v[180:181], 0, s[52:53]
	s_mov_b32 m0, s44
	s_nop 0
	global_load_lds_dwordx4 v[176:177], off
	v_lshl_add_u64 v[176:177], v[236:237], 0, s[52:53]
	s_add_i32 m0, s44, 0x2000
	s_nop 0
	global_load_lds_dwordx4 v[176:177], off
	v_lshl_add_u64 v[176:177], v[238:239], 0, s[52:53]
	s_mov_b32 m0, s97
	s_nop 0
	global_load_lds_dwordx4 v[176:177], off
	v_lshl_add_u64 v[176:177], v[240:241], 0, s[52:53]
	s_mov_b32 m0, s54
	s_nop 0
	global_load_lds_dwordx4 v[176:177], off
	s_waitcnt vmcnt(8)
	s_waitcnt lgkmcnt(0)
	s_barrier
	s_setprio 1
	s_waitcnt lgkmcnt(0)
	v_mfma_f32_16x16x32_bf16 v[60:63], v[156:159], v[204:207], v[60:63]
	v_mfma_f32_16x16x32_bf16 v[56:59], v[164:167], v[204:207], v[56:59]
	v_mfma_f32_16x16x32_bf16 v[44:47], v[156:159], v[212:215], v[44:47]
	v_mfma_f32_16x16x32_bf16 v[40:43], v[164:167], v[212:215], v[40:43]
	v_mfma_f32_16x16x32_bf16 v[28:31], v[156:159], v[220:223], v[28:31]
	v_mfma_f32_16x16x32_bf16 v[24:27], v[164:167], v[220:223], v[24:27]
	v_mfma_f32_16x16x32_bf16 v[12:15], v[156:159], v[228:231], v[12:15]
	v_mfma_f32_16x16x32_bf16 v[8:11], v[164:167], v[228:231], v[8:11]
	v_mfma_f32_16x16x32_bf16 v[60:63], v[160:163], v[208:211], v[60:63]
	v_mfma_f32_16x16x32_bf16 v[56:59], v[168:171], v[208:211], v[56:59]
	v_mfma_f32_16x16x32_bf16 v[44:47], v[160:163], v[216:219], v[44:47]
	v_mfma_f32_16x16x32_bf16 v[40:43], v[168:171], v[216:219], v[40:43]
	v_mfma_f32_16x16x32_bf16 v[28:31], v[160:163], v[224:227], v[28:31]
	v_mfma_f32_16x16x32_bf16 v[24:27], v[168:171], v[224:227], v[24:27]
	v_mfma_f32_16x16x32_bf16 v[12:15], v[160:163], v[232:235], v[12:15]
	v_mfma_f32_16x16x32_bf16 v[8:11], v[168:171], v[232:235], v[8:11]
	v_mfma_f32_16x16x32_bf16 v[52:55], v[172:175], v[204:207], v[52:55]
	v_mfma_f32_16x16x32_bf16 v[48:51], v[188:191], v[204:207], v[48:51]
	v_mfma_f32_16x16x32_bf16 v[36:39], v[172:175], v[212:215], v[36:39]
	v_mfma_f32_16x16x32_bf16 v[32:35], v[188:191], v[212:215], v[32:35]
	v_mfma_f32_16x16x32_bf16 v[20:23], v[172:175], v[220:223], v[20:23]
	v_mfma_f32_16x16x32_bf16 v[16:19], v[188:191], v[220:223], v[16:19]
	v_mfma_f32_16x16x32_bf16 v[4:7], v[172:175], v[228:231], v[4:7]
	v_mfma_f32_16x16x32_bf16 v[0:3], v[188:191], v[228:231], v[0:3]
	v_mfma_f32_16x16x32_bf16 v[52:55], v[184:187], v[208:211], v[52:55]
	v_mfma_f32_16x16x32_bf16 v[48:51], v[192:195], v[208:211], v[48:51]
	v_mfma_f32_16x16x32_bf16 v[36:39], v[184:187], v[216:219], v[36:39]
	v_mfma_f32_16x16x32_bf16 v[32:35], v[192:195], v[216:219], v[32:35]
	v_mfma_f32_16x16x32_bf16 v[20:23], v[184:187], v[224:227], v[20:23]
	v_mfma_f32_16x16x32_bf16 v[16:19], v[192:195], v[224:227], v[16:19]
	v_mfma_f32_16x16x32_bf16 v[4:7], v[184:187], v[232:235], v[4:7]
	v_mfma_f32_16x16x32_bf16 v[0:3], v[192:195], v[232:235], v[0:3]
	s_setprio 0
	s_barrier
	s_add_u32 s88, s88, 0x100
	s_addc_u32 s89, s89, 0
	s_add_u32 s15, s15, 0x100
	s_addc_u32 s16, s16, 0
	s_cmp_ge_i32 vcc_lo, s13
	s_mov_b32 s90, vcc_lo
	s_cbranch_scc0 .LBB0_624

.LBB0_725:
	s_add_i32 s82, s78, 2
	s_add_u32 s44, s76, 0x80
	s_addc_u32 s45, s77, 0
	s_add_i32 s58, 0, 0x10000
	s_cmp_eq_u32 s50, s78
	s_cselect_b32 s79, s9, s45
	s_cselect_b32 s78, s8, s44
	v_add_u32_e32 v140, s58, v143
	s_cselect_b32 s45, s75, s81
	s_cselect_b32 s44, s74, s80
	s_add_i32 s83, 0, 0x14000
	ds_read_b128 v[146:149], v140
	ds_read_b128 v[150:153], v140 offset:1024
	ds_read_b128 v[154:157], v140 offset:2048
	ds_read_b128 v[158:161], v140 offset:3072
	v_add_u32_e32 v140, s83, v143
	ds_read_b128 v[162:165], v140
	ds_read_b128 v[166:169], v140 offset:1024
	ds_read_b128 v[170:173], v140 offset:2048
	ds_read_b128 v[174:177], v140 offset:3072
	v_lshl_add_u64 v[140:141], s[76:77], 0, v[136:137]
	s_add_i32 m0, s23, 0xc000
	ds_read_b128 v[184:187], v145
	ds_read_b128 v[188:191], v145 offset:1024
	ds_read_b128 v[192:195], v145 offset:2048
	ds_read_b128 v[204:207], v145 offset:3072
	ds_read_b128 v[208:211], v145 offset:4096
	ds_read_b128 v[212:215], v145 offset:5120
	ds_read_b128 v[216:219], v145 offset:6144
	ds_read_b128 v[220:223], v145 offset:7168
	global_load_lds_dwordx4 v[140:141], off
	v_lshl_add_u64 v[140:141], s[76:77], 0, v[138:139]
	s_add_i32 m0, s23, 0xe000
	s_nop 0
	global_load_lds_dwordx4 v[140:141], off
	s_waitcnt vmcnt(8)
	s_waitcnt lgkmcnt(0)
	s_barrier
	s_setprio 1
	s_waitcnt lgkmcnt(0)
	v_mfma_f32_16x16x32_bf16 v[120:123], v[146:149], v[184:187], v[120:123]
	v_mfma_f32_16x16x32_bf16 v[124:127], v[154:157], v[184:187], v[124:127]
	v_mfma_f32_16x16x32_bf16 v[108:111], v[146:149], v[192:195], v[108:111]
	v_mfma_f32_16x16x32_bf16 v[104:107], v[154:157], v[192:195], v[104:107]
	v_mfma_f32_16x16x32_bf16 v[92:95], v[146:149], v[208:211], v[92:95]
	v_mfma_f32_16x16x32_bf16 v[88:91], v[154:157], v[208:211], v[88:91]
	v_mfma_f32_16x16x32_bf16 v[76:79], v[146:149], v[216:219], v[76:79]
	v_mfma_f32_16x16x32_bf16 v[72:75], v[154:157], v[216:219], v[72:75]
	v_mfma_f32_16x16x32_bf16 v[120:123], v[150:153], v[188:191], v[120:123]
	v_mfma_f32_16x16x32_bf16 v[124:127], v[158:161], v[188:191], v[124:127]
	v_mfma_f32_16x16x32_bf16 v[108:111], v[150:153], v[204:207], v[108:111]
	v_mfma_f32_16x16x32_bf16 v[104:107], v[158:161], v[204:207], v[104:107]
	v_mfma_f32_16x16x32_bf16 v[92:95], v[150:153], v[212:215], v[92:95]
	v_mfma_f32_16x16x32_bf16 v[88:91], v[158:161], v[212:215], v[88:91]
	v_mfma_f32_16x16x32_bf16 v[76:79], v[150:153], v[220:223], v[76:79]
	v_mfma_f32_16x16x32_bf16 v[72:75], v[158:161], v[220:223], v[72:75]
	v_mfma_f32_16x16x32_bf16 v[116:119], v[162:165], v[184:187], v[116:119]
	v_mfma_f32_16x16x32_bf16 v[112:115], v[170:173], v[184:187], v[112:115]
	v_mfma_f32_16x16x32_bf16 v[100:103], v[162:165], v[192:195], v[100:103]
	v_mfma_f32_16x16x32_bf16 v[96:99], v[170:173], v[192:195], v[96:99]
	v_mfma_f32_16x16x32_bf16 v[84:87], v[162:165], v[208:211], v[84:87]
	v_mfma_f32_16x16x32_bf16 v[80:83], v[170:173], v[208:211], v[80:83]
	v_mfma_f32_16x16x32_bf16 v[68:71], v[162:165], v[216:219], v[68:71]
	v_mfma_f32_16x16x32_bf16 v[64:67], v[170:173], v[216:219], v[64:67]
	v_mfma_f32_16x16x32_bf16 v[116:119], v[166:169], v[188:191], v[116:119]
	v_mfma_f32_16x16x32_bf16 v[112:115], v[174:177], v[188:191], v[112:115]
	v_mfma_f32_16x16x32_bf16 v[100:103], v[166:169], v[204:207], v[100:103]
	v_mfma_f32_16x16x32_bf16 v[96:99], v[174:177], v[204:207], v[96:99]
	v_mfma_f32_16x16x32_bf16 v[84:87], v[166:169], v[212:215], v[84:87]
	v_mfma_f32_16x16x32_bf16 v[80:83], v[174:177], v[212:215], v[80:83]
	v_mfma_f32_16x16x32_bf16 v[68:71], v[166:169], v[220:223], v[68:71]
	v_mfma_f32_16x16x32_bf16 v[64:67], v[174:177], v[220:223], v[64:67]
	s_setprio 0
	s_barrier
	s_add_i32 s58, s58, s22
	v_lshl_add_u64 v[140:141], s[44:45], 0, v[128:129]
	s_mov_b32 m0, s58
	ds_read_b128 v[184:187], v145 offset:16384
	ds_read_b128 v[188:191], v145 offset:17408
	ds_read_b128 v[192:195], v145 offset:18432
	ds_read_b128 v[204:207], v145 offset:19456
	ds_read_b128 v[208:211], v145 offset:20480
	ds_read_b128 v[212:215], v145 offset:21504
	ds_read_b128 v[216:219], v145 offset:22528
	ds_read_b128 v[220:223], v145 offset:23552
	global_load_lds_dwordx4 v[140:141], off
	s_add_i32 m0, s58, 0x2000
	v_lshl_add_u64 v[178:179], s[44:45], 0, v[130:131]
	s_add_u32 s44, s44, s10
	s_addc_u32 s45, s45, s11
	s_add_i32 s58, s83, s22
	global_load_lds_dwordx4 v[178:179], off
	v_lshl_add_u64 v[180:181], s[44:45], 0, v[128:129]
	s_mov_b32 m0, s58
	v_lshl_add_u64 v[224:225], s[44:45], 0, v[130:131]
	global_load_lds_dwordx4 v[180:181], off
	s_add_i32 m0, s58, 0x2000
	v_lshl_add_u64 v[226:227], s[78:79], 0, v[134:135]
	global_load_lds_dwordx4 v[224:225], off
	s_mov_b32 m0, s23
	v_lshl_add_u64 v[228:229], s[78:79], 0, v[132:133]
	global_load_lds_dwordx4 v[226:227], off
	s_mov_b32 m0, s29
	s_nop 0
	global_load_lds_dwordx4 v[228:229], off
	s_waitcnt vmcnt(8)
	s_waitcnt lgkmcnt(0)
	s_barrier
	s_setprio 1
	s_waitcnt lgkmcnt(0)
	v_mfma_f32_16x16x32_bf16 v[60:63], v[146:149], v[184:187], v[60:63]
	v_mfma_f32_16x16x32_bf16 v[56:59], v[154:157], v[184:187], v[56:59]
	v_mfma_f32_16x16x32_bf16 v[44:47], v[146:149], v[192:195], v[44:47]
	v_mfma_f32_16x16x32_bf16 v[40:43], v[154:157], v[192:195], v[40:43]
	v_mfma_f32_16x16x32_bf16 v[28:31], v[146:149], v[208:211], v[28:31]
	v_mfma_f32_16x16x32_bf16 v[24:27], v[154:157], v[208:211], v[24:27]
	v_mfma_f32_16x16x32_bf16 v[12:15], v[146:149], v[216:219], v[12:15]
	v_mfma_f32_16x16x32_bf16 v[8:11], v[154:157], v[216:219], v[8:11]
	v_mfma_f32_16x16x32_bf16 v[60:63], v[150:153], v[188:191], v[60:63]
	v_mfma_f32_16x16x32_bf16 v[56:59], v[158:161], v[188:191], v[56:59]
	v_mfma_f32_16x16x32_bf16 v[44:47], v[150:153], v[204:207], v[44:47]
	v_mfma_f32_16x16x32_bf16 v[40:43], v[158:161], v[204:207], v[40:43]
	v_mfma_f32_16x16x32_bf16 v[28:31], v[150:153], v[212:215], v[28:31]
	v_mfma_f32_16x16x32_bf16 v[24:27], v[158:161], v[212:215], v[24:27]
	v_mfma_f32_16x16x32_bf16 v[12:15], v[150:153], v[220:223], v[12:15]
	v_mfma_f32_16x16x32_bf16 v[8:11], v[158:161], v[220:223], v[8:11]
	v_mfma_f32_16x16x32_bf16 v[52:55], v[162:165], v[184:187], v[52:55]
	v_mfma_f32_16x16x32_bf16 v[48:51], v[170:173], v[184:187], v[48:51]
	v_mfma_f32_16x16x32_bf16 v[36:39], v[162:165], v[192:195], v[36:39]
	v_mfma_f32_16x16x32_bf16 v[32:35], v[170:173], v[192:195], v[32:35]
	v_mfma_f32_16x16x32_bf16 v[20:23], v[162:165], v[208:211], v[20:23]
	v_mfma_f32_16x16x32_bf16 v[16:19], v[170:173], v[208:211], v[16:19]
	v_mfma_f32_16x16x32_bf16 v[4:7], v[162:165], v[216:219], v[4:7]
	v_mfma_f32_16x16x32_bf16 v[0:3], v[170:173], v[216:219], v[0:3]
	v_mfma_f32_16x16x32_bf16 v[52:55], v[166:169], v[188:191], v[52:55]
	v_mfma_f32_16x16x32_bf16 v[48:51], v[174:177], v[188:191], v[48:51]
	v_mfma_f32_16x16x32_bf16 v[36:39], v[166:169], v[204:207], v[36:39]
	v_mfma_f32_16x16x32_bf16 v[32:35], v[174:177], v[204:207], v[32:35]
	v_mfma_f32_16x16x32_bf16 v[20:23], v[166:169], v[212:215], v[20:23]
	v_mfma_f32_16x16x32_bf16 v[16:19], v[174:177], v[212:215], v[16:19]
	v_mfma_f32_16x16x32_bf16 v[4:7], v[166:169], v[220:223], v[4:7]
	v_mfma_f32_16x16x32_bf16 v[0:3], v[174:177], v[220:223], v[0:3]
	s_setprio 0
	s_barrier
	s_add_i32 s58, 0, 0x18000
	s_add_i32 s83, 0, 0x1c000
	v_add_u32_e32 v158, s58, v143
	v_add_u32_e32 v174, s83, v143
	ds_read_b128 v[146:149], v158
	ds_read_b128 v[150:153], v158 offset:1024
	ds_read_b128 v[154:157], v158 offset:2048
	ds_read_b128 v[158:161], v158 offset:3072
	ds_read_b128 v[162:165], v174
	ds_read_b128 v[166:169], v174 offset:1024
	ds_read_b128 v[170:173], v174 offset:2048
	ds_read_b128 v[174:177], v174 offset:3072
	s_add_u32 s44, s78, s10
	s_addc_u32 s45, s79, s11
	s_mov_b32 m0, s39
	v_lshl_add_u64 v[230:231], s[44:45], 0, v[134:135]
	ds_read_b128 v[184:187], v145 offset:32768
	ds_read_b128 v[188:191], v145 offset:33792
	ds_read_b128 v[192:195], v145 offset:34816
	ds_read_b128 v[204:207], v145 offset:35840
	ds_read_b128 v[208:211], v145 offset:36864
	ds_read_b128 v[212:215], v145 offset:37888
	ds_read_b128 v[216:219], v145 offset:38912
	ds_read_b128 v[220:223], v145 offset:39936
	global_load_lds_dwordx4 v[230:231], off
	v_lshl_add_u64 v[230:231], s[44:45], 0, v[132:133]
	s_mov_b32 m0, s40
	s_nop 0
	global_load_lds_dwordx4 v[230:231], off
	s_waitcnt vmcnt(8)
	s_waitcnt lgkmcnt(0)
	s_barrier
	s_setprio 1
	s_waitcnt lgkmcnt(0)
	v_mfma_f32_16x16x32_bf16 v[120:123], v[146:149], v[184:187], v[120:123]
	v_mfma_f32_16x16x32_bf16 v[124:127], v[154:157], v[184:187], v[124:127]
	v_mfma_f32_16x16x32_bf16 v[108:111], v[146:149], v[192:195], v[108:111]
	v_mfma_f32_16x16x32_bf16 v[104:107], v[154:157], v[192:195], v[104:107]
	v_mfma_f32_16x16x32_bf16 v[92:95], v[146:149], v[208:211], v[92:95]
	v_mfma_f32_16x16x32_bf16 v[88:91], v[154:157], v[208:211], v[88:91]
	v_mfma_f32_16x16x32_bf16 v[76:79], v[146:149], v[216:219], v[76:79]
	v_mfma_f32_16x16x32_bf16 v[72:75], v[154:157], v[216:219], v[72:75]
	v_mfma_f32_16x16x32_bf16 v[120:123], v[150:153], v[188:191], v[120:123]
	v_mfma_f32_16x16x32_bf16 v[124:127], v[158:161], v[188:191], v[124:127]
	v_mfma_f32_16x16x32_bf16 v[108:111], v[150:153], v[204:207], v[108:111]
	v_mfma_f32_16x16x32_bf16 v[104:107], v[158:161], v[204:207], v[104:107]
	v_mfma_f32_16x16x32_bf16 v[92:95], v[150:153], v[212:215], v[92:95]
	v_mfma_f32_16x16x32_bf16 v[88:91], v[158:161], v[212:215], v[88:91]
	v_mfma_f32_16x16x32_bf16 v[76:79], v[150:153], v[220:223], v[76:79]
	v_mfma_f32_16x16x32_bf16 v[72:75], v[158:161], v[220:223], v[72:75]
	v_mfma_f32_16x16x32_bf16 v[116:119], v[162:165], v[184:187], v[116:119]
	v_mfma_f32_16x16x32_bf16 v[112:115], v[170:173], v[184:187], v[112:115]
	v_mfma_f32_16x16x32_bf16 v[100:103], v[162:165], v[192:195], v[100:103]
	v_mfma_f32_16x16x32_bf16 v[96:99], v[170:173], v[192:195], v[96:99]
	v_mfma_f32_16x16x32_bf16 v[84:87], v[162:165], v[208:211], v[84:87]
	v_mfma_f32_16x16x32_bf16 v[80:83], v[170:173], v[208:211], v[80:83]
	v_mfma_f32_16x16x32_bf16 v[68:71], v[162:165], v[216:219], v[68:71]
	v_mfma_f32_16x16x32_bf16 v[64:67], v[170:173], v[216:219], v[64:67]
	v_mfma_f32_16x16x32_bf16 v[116:119], v[166:169], v[188:191], v[116:119]
	v_mfma_f32_16x16x32_bf16 v[112:115], v[174:177], v[188:191], v[112:115]
	v_mfma_f32_16x16x32_bf16 v[100:103], v[166:169], v[204:207], v[100:103]
	v_mfma_f32_16x16x32_bf16 v[96:99], v[174:177], v[204:207], v[96:99]
	v_mfma_f32_16x16x32_bf16 v[84:87], v[166:169], v[212:215], v[84:87]
	v_mfma_f32_16x16x32_bf16 v[80:83], v[174:177], v[212:215], v[80:83]
	v_mfma_f32_16x16x32_bf16 v[68:71], v[166:169], v[220:223], v[68:71]
	v_mfma_f32_16x16x32_bf16 v[64:67], v[174:177], v[220:223], v[64:67]
	s_setprio 0
	s_barrier
	s_add_i32 s44, s58, s22
	v_lshl_add_u64 v[140:141], v[140:141], 0, s[52:53]
	s_mov_b32 m0, s44
	ds_read_b128 v[184:187], v145 offset:49152
	ds_read_b128 v[188:191], v145 offset:50176
	ds_read_b128 v[192:195], v145 offset:51200
	ds_read_b128 v[204:207], v145 offset:52224
	ds_read_b128 v[208:211], v145 offset:53248
	ds_read_b128 v[212:215], v145 offset:54272
	ds_read_b128 v[216:219], v145 offset:55296
	ds_read_b128 v[220:223], v145 offset:56320
	global_load_lds_dwordx4 v[140:141], off
	v_lshl_add_u64 v[140:141], v[178:179], 0, s[52:53]
	s_add_i32 m0, s44, 0x2000
	s_add_i32 s44, s83, s22
	global_load_lds_dwordx4 v[140:141], off
	v_lshl_add_u64 v[140:141], v[180:181], 0, s[52:53]
	s_mov_b32 m0, s44
	s_nop 0
	global_load_lds_dwordx4 v[140:141], off
	v_lshl_add_u64 v[140:141], v[224:225], 0, s[52:53]
	s_add_i32 m0, s44, 0x2000
	s_nop 0
	global_load_lds_dwordx4 v[140:141], off
	v_lshl_add_u64 v[140:141], v[226:227], 0, s[52:53]
	s_mov_b32 m0, s46
	s_nop 0
	global_load_lds_dwordx4 v[140:141], off
	v_lshl_add_u64 v[140:141], v[228:229], 0, s[52:53]
	s_mov_b32 m0, s47
	s_nop 0
	global_load_lds_dwordx4 v[140:141], off
	s_waitcnt vmcnt(8)
	s_waitcnt lgkmcnt(0)
	s_barrier
	s_setprio 1
	s_waitcnt lgkmcnt(0)
	v_mfma_f32_16x16x32_bf16 v[60:63], v[146:149], v[184:187], v[60:63]
	v_mfma_f32_16x16x32_bf16 v[56:59], v[154:157], v[184:187], v[56:59]
	v_mfma_f32_16x16x32_bf16 v[44:47], v[146:149], v[192:195], v[44:47]
	v_mfma_f32_16x16x32_bf16 v[40:43], v[154:157], v[192:195], v[40:43]
	v_mfma_f32_16x16x32_bf16 v[28:31], v[146:149], v[208:211], v[28:31]
	v_mfma_f32_16x16x32_bf16 v[24:27], v[154:157], v[208:211], v[24:27]
	v_mfma_f32_16x16x32_bf16 v[12:15], v[146:149], v[216:219], v[12:15]
	v_mfma_f32_16x16x32_bf16 v[8:11], v[154:157], v[216:219], v[8:11]
	v_mfma_f32_16x16x32_bf16 v[60:63], v[150:153], v[188:191], v[60:63]
	v_mfma_f32_16x16x32_bf16 v[56:59], v[158:161], v[188:191], v[56:59]
	v_mfma_f32_16x16x32_bf16 v[44:47], v[150:153], v[204:207], v[44:47]
	v_mfma_f32_16x16x32_bf16 v[40:43], v[158:161], v[204:207], v[40:43]
	v_mfma_f32_16x16x32_bf16 v[28:31], v[150:153], v[212:215], v[28:31]
	v_mfma_f32_16x16x32_bf16 v[24:27], v[158:161], v[212:215], v[24:27]
	v_mfma_f32_16x16x32_bf16 v[12:15], v[150:153], v[220:223], v[12:15]
	v_mfma_f32_16x16x32_bf16 v[8:11], v[158:161], v[220:223], v[8:11]
	v_mfma_f32_16x16x32_bf16 v[52:55], v[162:165], v[184:187], v[52:55]
	v_mfma_f32_16x16x32_bf16 v[48:51], v[170:173], v[184:187], v[48:51]
	v_mfma_f32_16x16x32_bf16 v[36:39], v[162:165], v[192:195], v[36:39]
	v_mfma_f32_16x16x32_bf16 v[32:35], v[170:173], v[192:195], v[32:35]
	v_mfma_f32_16x16x32_bf16 v[20:23], v[162:165], v[208:211], v[20:23]
	v_mfma_f32_16x16x32_bf16 v[16:19], v[170:173], v[208:211], v[16:19]
	v_mfma_f32_16x16x32_bf16 v[4:7], v[162:165], v[216:219], v[4:7]
	v_mfma_f32_16x16x32_bf16 v[0:3], v[170:173], v[216:219], v[0:3]
	v_mfma_f32_16x16x32_bf16 v[52:55], v[166:169], v[188:191], v[52:55]
	v_mfma_f32_16x16x32_bf16 v[48:51], v[174:177], v[188:191], v[48:51]
	v_mfma_f32_16x16x32_bf16 v[36:39], v[166:169], v[204:207], v[36:39]
	v_mfma_f32_16x16x32_bf16 v[32:35], v[174:177], v[204:207], v[32:35]
	v_mfma_f32_16x16x32_bf16 v[20:23], v[166:169], v[212:215], v[20:23]
	v_mfma_f32_16x16x32_bf16 v[16:19], v[174:177], v[212:215], v[16:19]
	v_mfma_f32_16x16x32_bf16 v[4:7], v[166:169], v[220:223], v[4:7]
	v_mfma_f32_16x16x32_bf16 v[0:3], v[174:177], v[220:223], v[0:3]
	s_setprio 0
	s_barrier
	s_add_u32 s76, s76, 0x100
	s_addc_u32 s77, s77, 0
	s_add_u32 s80, s80, 0x100
	s_addc_u32 s81, s81, 0
	s_cmp_ge_i32 s82, s41
	s_mov_b32 s78, s82
	s_cbranch_scc0 .LBB0_725

.LBB0_746:
	s_add_i32 s85, s82, 2
	s_add_u32 s44, s8, 0x80
	s_addc_u32 s45, s9, 0
	s_add_i32 s58, 0, 0x10000
	s_cmp_eq_u32 s50, s82
	s_cselect_b32 s83, s79, s45
	s_cselect_b32 s82, s78, s44
	v_add_u32_e32 v128, s58, v186
	s_cselect_b32 s45, s81, s84
	s_cselect_b32 s44, s80, s16
	s_add_i32 s88, 0, 0x14000
	ds_read_b128 v[130:133], v128
	ds_read_b128 v[134:137], v128 offset:1024
	ds_read_b128 v[138:141], v128 offset:2048
	ds_read_b128 v[142:145], v128 offset:3072
	v_add_u32_e32 v128, s88, v186
	ds_read_b128 v[146:149], v128
	ds_read_b128 v[150:153], v128 offset:1024
	ds_read_b128 v[154:157], v128 offset:2048
	ds_read_b128 v[158:161], v128 offset:3072
	v_lshl_add_u64 v[162:163], s[8:9], 0, v[172:173]
	s_add_i32 m0, s23, 0xc000
	ds_read_b128 v[204:207], v192
	ds_read_b128 v[208:211], v192 offset:1024
	ds_read_b128 v[212:215], v192 offset:2048
	ds_read_b128 v[216:219], v192 offset:3072
	ds_read_b128 v[220:223], v192 offset:4096
	ds_read_b128 v[224:227], v192 offset:5120
	ds_read_b128 v[228:231], v192 offset:6144
	ds_read_b128 v[232:235], v192 offset:7168
	global_load_lds_dwordx4 v[162:163], off
	v_lshl_add_u64 v[162:163], s[8:9], 0, v[174:175]
	s_add_i32 m0, s23, 0xe000
	s_nop 0
	global_load_lds_dwordx4 v[162:163], off
	s_waitcnt vmcnt(8)
	s_waitcnt lgkmcnt(0)
	s_barrier
	s_setprio 1
	s_waitcnt lgkmcnt(0)
	v_mfma_f32_16x16x32_bf16 v[124:127], v[130:133], v[204:207], v[124:127]
	v_mfma_f32_16x16x32_bf16 v[120:123], v[138:141], v[204:207], v[120:123]
	v_mfma_f32_16x16x32_bf16 v[108:111], v[130:133], v[212:215], v[108:111]
	v_mfma_f32_16x16x32_bf16 v[104:107], v[138:141], v[212:215], v[104:107]
	v_mfma_f32_16x16x32_bf16 v[92:95], v[130:133], v[220:223], v[92:95]
	v_mfma_f32_16x16x32_bf16 v[88:91], v[138:141], v[220:223], v[88:91]
	v_mfma_f32_16x16x32_bf16 v[76:79], v[130:133], v[228:231], v[76:79]
	v_mfma_f32_16x16x32_bf16 v[72:75], v[138:141], v[228:231], v[72:75]
	v_mfma_f32_16x16x32_bf16 v[124:127], v[134:137], v[208:211], v[124:127]
	v_mfma_f32_16x16x32_bf16 v[120:123], v[142:145], v[208:211], v[120:123]
	v_mfma_f32_16x16x32_bf16 v[108:111], v[134:137], v[216:219], v[108:111]
	v_mfma_f32_16x16x32_bf16 v[104:107], v[142:145], v[216:219], v[104:107]
	v_mfma_f32_16x16x32_bf16 v[92:95], v[134:137], v[224:227], v[92:95]
	v_mfma_f32_16x16x32_bf16 v[88:91], v[142:145], v[224:227], v[88:91]
	v_mfma_f32_16x16x32_bf16 v[76:79], v[134:137], v[232:235], v[76:79]
	v_mfma_f32_16x16x32_bf16 v[72:75], v[142:145], v[232:235], v[72:75]
	v_mfma_f32_16x16x32_bf16 v[116:119], v[146:149], v[204:207], v[116:119]
	v_mfma_f32_16x16x32_bf16 v[112:115], v[154:157], v[204:207], v[112:115]
	v_mfma_f32_16x16x32_bf16 v[100:103], v[146:149], v[212:215], v[100:103]
	v_mfma_f32_16x16x32_bf16 v[96:99], v[154:157], v[212:215], v[96:99]
	v_mfma_f32_16x16x32_bf16 v[84:87], v[146:149], v[220:223], v[84:87]
	v_mfma_f32_16x16x32_bf16 v[80:83], v[154:157], v[220:223], v[80:83]
	v_mfma_f32_16x16x32_bf16 v[68:71], v[146:149], v[228:231], v[68:71]
	v_mfma_f32_16x16x32_bf16 v[64:67], v[154:157], v[228:231], v[64:67]
	v_mfma_f32_16x16x32_bf16 v[116:119], v[150:153], v[208:211], v[116:119]
	v_mfma_f32_16x16x32_bf16 v[112:115], v[158:161], v[208:211], v[112:115]
	v_mfma_f32_16x16x32_bf16 v[100:103], v[150:153], v[216:219], v[100:103]
	v_mfma_f32_16x16x32_bf16 v[96:99], v[158:161], v[216:219], v[96:99]
	v_mfma_f32_16x16x32_bf16 v[84:87], v[150:153], v[224:227], v[84:87]
	v_mfma_f32_16x16x32_bf16 v[80:83], v[158:161], v[224:227], v[80:83]
	v_mfma_f32_16x16x32_bf16 v[68:71], v[150:153], v[232:235], v[68:71]
	v_mfma_f32_16x16x32_bf16 v[64:67], v[158:161], v[232:235], v[64:67]
	s_setprio 0
	s_barrier
	s_add_i32 s58, s58, s22
	v_lshl_add_u64 v[162:163], s[44:45], 0, v[168:169]
	s_mov_b32 m0, s58
	ds_read_b128 v[204:207], v192 offset:16384
	ds_read_b128 v[208:211], v192 offset:17408
	ds_read_b128 v[212:215], v192 offset:18432
	ds_read_b128 v[216:219], v192 offset:19456
	ds_read_b128 v[220:223], v192 offset:20480
	ds_read_b128 v[224:227], v192 offset:21504
	ds_read_b128 v[228:231], v192 offset:22528
	ds_read_b128 v[232:235], v192 offset:23552
	global_load_lds_dwordx4 v[162:163], off
	s_add_i32 m0, s58, 0x2000
	v_lshl_add_u64 v[176:177], s[44:45], 0, v[164:165]
	s_add_u32 s44, s44, s10
	s_addc_u32 s45, s45, s11
	s_add_i32 s58, s88, s22
	global_load_lds_dwordx4 v[176:177], off
	v_lshl_add_u64 v[178:179], s[44:45], 0, v[168:169]
	s_mov_b32 m0, s58
	v_lshl_add_u64 v[180:181], s[44:45], 0, v[164:165]
	global_load_lds_dwordx4 v[178:179], off
	s_add_i32 m0, s58, 0x2000
	v_lshl_add_u64 v[194:195], s[82:83], 0, v[170:171]
	global_load_lds_dwordx4 v[180:181], off
	s_mov_b32 m0, s23
	v_lshl_add_u64 v[236:237], s[82:83], 0, v[166:167]
	global_load_lds_dwordx4 v[194:195], off
	s_mov_b32 m0, s29
	s_nop 0
	global_load_lds_dwordx4 v[236:237], off
	s_waitcnt vmcnt(8)
	s_waitcnt lgkmcnt(0)
	s_barrier
	s_setprio 1
	s_waitcnt lgkmcnt(0)
	v_mfma_f32_16x16x32_bf16 v[60:63], v[130:133], v[204:207], v[60:63]
	v_mfma_f32_16x16x32_bf16 v[56:59], v[138:141], v[204:207], v[56:59]
	v_mfma_f32_16x16x32_bf16 v[44:47], v[130:133], v[212:215], v[44:47]
	v_mfma_f32_16x16x32_bf16 v[40:43], v[138:141], v[212:215], v[40:43]
	v_mfma_f32_16x16x32_bf16 v[28:31], v[130:133], v[220:223], v[28:31]
	v_mfma_f32_16x16x32_bf16 v[24:27], v[138:141], v[220:223], v[24:27]
	v_mfma_f32_16x16x32_bf16 v[12:15], v[130:133], v[228:231], v[12:15]
	v_mfma_f32_16x16x32_bf16 v[8:11], v[138:141], v[228:231], v[8:11]
	v_mfma_f32_16x16x32_bf16 v[60:63], v[134:137], v[208:211], v[60:63]
	v_mfma_f32_16x16x32_bf16 v[56:59], v[142:145], v[208:211], v[56:59]
	v_mfma_f32_16x16x32_bf16 v[44:47], v[134:137], v[216:219], v[44:47]
	v_mfma_f32_16x16x32_bf16 v[40:43], v[142:145], v[216:219], v[40:43]
	v_mfma_f32_16x16x32_bf16 v[28:31], v[134:137], v[224:227], v[28:31]
	v_mfma_f32_16x16x32_bf16 v[24:27], v[142:145], v[224:227], v[24:27]
	v_mfma_f32_16x16x32_bf16 v[12:15], v[134:137], v[232:235], v[12:15]
	v_mfma_f32_16x16x32_bf16 v[8:11], v[142:145], v[232:235], v[8:11]
	v_mfma_f32_16x16x32_bf16 v[52:55], v[146:149], v[204:207], v[52:55]
	v_mfma_f32_16x16x32_bf16 v[48:51], v[154:157], v[204:207], v[48:51]
	v_mfma_f32_16x16x32_bf16 v[36:39], v[146:149], v[212:215], v[36:39]
	v_mfma_f32_16x16x32_bf16 v[32:35], v[154:157], v[212:215], v[32:35]
	v_mfma_f32_16x16x32_bf16 v[20:23], v[146:149], v[220:223], v[20:23]
	v_mfma_f32_16x16x32_bf16 v[16:19], v[154:157], v[220:223], v[16:19]
	v_mfma_f32_16x16x32_bf16 v[4:7], v[146:149], v[228:231], v[4:7]
	v_mfma_f32_16x16x32_bf16 v[0:3], v[154:157], v[228:231], v[0:3]
	v_mfma_f32_16x16x32_bf16 v[52:55], v[150:153], v[208:211], v[52:55]
	v_mfma_f32_16x16x32_bf16 v[48:51], v[158:161], v[208:211], v[48:51]
	v_mfma_f32_16x16x32_bf16 v[36:39], v[150:153], v[216:219], v[36:39]
	v_mfma_f32_16x16x32_bf16 v[32:35], v[158:161], v[216:219], v[32:35]
	v_mfma_f32_16x16x32_bf16 v[20:23], v[150:153], v[224:227], v[20:23]
	v_mfma_f32_16x16x32_bf16 v[16:19], v[158:161], v[224:227], v[16:19]
	v_mfma_f32_16x16x32_bf16 v[4:7], v[150:153], v[232:235], v[4:7]
	v_mfma_f32_16x16x32_bf16 v[0:3], v[158:161], v[232:235], v[0:3]
	s_setprio 0
	s_barrier
	s_add_i32 s58, 0, 0x18000
	v_add_u32_e32 v128, s58, v186
	s_add_i32 s88, 0, 0x1c000
	ds_read_b128 v[130:133], v128
	ds_read_b128 v[134:137], v128 offset:1024
	ds_read_b128 v[138:141], v128 offset:2048
	ds_read_b128 v[142:145], v128 offset:3072
	v_add_u32_e32 v128, s88, v186
	ds_read_b128 v[146:149], v128
	ds_read_b128 v[150:153], v128 offset:1024
	ds_read_b128 v[154:157], v128 offset:2048
	ds_read_b128 v[158:161], v128 offset:3072
	s_add_u32 s44, s82, s10
	s_addc_u32 s45, s83, s11
	s_mov_b32 m0, s39
	v_lshl_add_u64 v[238:239], s[44:45], 0, v[170:171]
	ds_read_b128 v[204:207], v192 offset:32768
	ds_read_b128 v[208:211], v192 offset:33792
	ds_read_b128 v[212:215], v192 offset:34816
	ds_read_b128 v[216:219], v192 offset:35840
	ds_read_b128 v[220:223], v192 offset:36864
	ds_read_b128 v[224:227], v192 offset:37888
	ds_read_b128 v[228:231], v192 offset:38912
	ds_read_b128 v[232:235], v192 offset:39936
	global_load_lds_dwordx4 v[238:239], off
	v_lshl_add_u64 v[238:239], s[44:45], 0, v[166:167]
	s_mov_b32 m0, s40
	s_nop 0
	global_load_lds_dwordx4 v[238:239], off
	s_waitcnt vmcnt(8)
	s_waitcnt lgkmcnt(0)
	s_barrier
	s_setprio 1
	s_waitcnt lgkmcnt(0)
	v_mfma_f32_16x16x32_bf16 v[124:127], v[130:133], v[204:207], v[124:127]
	v_mfma_f32_16x16x32_bf16 v[120:123], v[138:141], v[204:207], v[120:123]
	v_mfma_f32_16x16x32_bf16 v[108:111], v[130:133], v[212:215], v[108:111]
	v_mfma_f32_16x16x32_bf16 v[104:107], v[138:141], v[212:215], v[104:107]
	v_mfma_f32_16x16x32_bf16 v[92:95], v[130:133], v[220:223], v[92:95]
	v_mfma_f32_16x16x32_bf16 v[88:91], v[138:141], v[220:223], v[88:91]
	v_mfma_f32_16x16x32_bf16 v[76:79], v[130:133], v[228:231], v[76:79]
	v_mfma_f32_16x16x32_bf16 v[72:75], v[138:141], v[228:231], v[72:75]
	v_mfma_f32_16x16x32_bf16 v[124:127], v[134:137], v[208:211], v[124:127]
	v_mfma_f32_16x16x32_bf16 v[120:123], v[142:145], v[208:211], v[120:123]
	v_mfma_f32_16x16x32_bf16 v[108:111], v[134:137], v[216:219], v[108:111]
	v_mfma_f32_16x16x32_bf16 v[104:107], v[142:145], v[216:219], v[104:107]
	v_mfma_f32_16x16x32_bf16 v[92:95], v[134:137], v[224:227], v[92:95]
	v_mfma_f32_16x16x32_bf16 v[88:91], v[142:145], v[224:227], v[88:91]
	v_mfma_f32_16x16x32_bf16 v[76:79], v[134:137], v[232:235], v[76:79]
	v_mfma_f32_16x16x32_bf16 v[72:75], v[142:145], v[232:235], v[72:75]
	v_mfma_f32_16x16x32_bf16 v[116:119], v[146:149], v[204:207], v[116:119]
	v_mfma_f32_16x16x32_bf16 v[112:115], v[154:157], v[204:207], v[112:115]
	v_mfma_f32_16x16x32_bf16 v[100:103], v[146:149], v[212:215], v[100:103]
	v_mfma_f32_16x16x32_bf16 v[96:99], v[154:157], v[212:215], v[96:99]
	v_mfma_f32_16x16x32_bf16 v[84:87], v[146:149], v[220:223], v[84:87]
	v_mfma_f32_16x16x32_bf16 v[80:83], v[154:157], v[220:223], v[80:83]
	v_mfma_f32_16x16x32_bf16 v[68:71], v[146:149], v[228:231], v[68:71]
	v_mfma_f32_16x16x32_bf16 v[64:67], v[154:157], v[228:231], v[64:67]
	v_mfma_f32_16x16x32_bf16 v[116:119], v[150:153], v[208:211], v[116:119]
	v_mfma_f32_16x16x32_bf16 v[112:115], v[158:161], v[208:211], v[112:115]
	v_mfma_f32_16x16x32_bf16 v[100:103], v[150:153], v[216:219], v[100:103]
	v_mfma_f32_16x16x32_bf16 v[96:99], v[158:161], v[216:219], v[96:99]
	v_mfma_f32_16x16x32_bf16 v[84:87], v[150:153], v[224:227], v[84:87]
	v_mfma_f32_16x16x32_bf16 v[80:83], v[158:161], v[224:227], v[80:83]
	v_mfma_f32_16x16x32_bf16 v[68:71], v[150:153], v[232:235], v[68:71]
	v_mfma_f32_16x16x32_bf16 v[64:67], v[158:161], v[232:235], v[64:67]
	s_setprio 0
	s_barrier
	s_add_i32 s44, s58, s22
	v_lshl_add_u64 v[162:163], v[162:163], 0, s[52:53]
	s_mov_b32 m0, s44
	ds_read_b128 v[204:207], v192 offset:49152
	ds_read_b128 v[208:211], v192 offset:50176
	ds_read_b128 v[212:215], v192 offset:51200
	ds_read_b128 v[216:219], v192 offset:52224
	ds_read_b128 v[220:223], v192 offset:53248
	ds_read_b128 v[224:227], v192 offset:54272
	ds_read_b128 v[228:231], v192 offset:55296
	ds_read_b128 v[232:235], v192 offset:56320
	global_load_lds_dwordx4 v[162:163], off
	v_lshl_add_u64 v[162:163], v[176:177], 0, s[52:53]
	s_add_i32 m0, s44, 0x2000
	s_add_i32 s44, s88, s22
	global_load_lds_dwordx4 v[162:163], off
	v_lshl_add_u64 v[162:163], v[178:179], 0, s[52:53]
	s_mov_b32 m0, s44
	s_nop 0
	global_load_lds_dwordx4 v[162:163], off
	v_lshl_add_u64 v[162:163], v[180:181], 0, s[52:53]
	s_add_i32 m0, s44, 0x2000
	s_nop 0
	global_load_lds_dwordx4 v[162:163], off
	v_lshl_add_u64 v[162:163], v[194:195], 0, s[52:53]
	s_mov_b32 m0, s46
	s_nop 0
	global_load_lds_dwordx4 v[162:163], off
	v_lshl_add_u64 v[162:163], v[236:237], 0, s[52:53]
	s_mov_b32 m0, s47
	s_nop 0
	global_load_lds_dwordx4 v[162:163], off
	s_waitcnt vmcnt(8)
	s_waitcnt lgkmcnt(0)
	s_barrier
	s_setprio 1
	s_waitcnt lgkmcnt(0)
	v_mfma_f32_16x16x32_bf16 v[60:63], v[130:133], v[204:207], v[60:63]
	v_mfma_f32_16x16x32_bf16 v[56:59], v[138:141], v[204:207], v[56:59]
	v_mfma_f32_16x16x32_bf16 v[44:47], v[130:133], v[212:215], v[44:47]
	v_mfma_f32_16x16x32_bf16 v[40:43], v[138:141], v[212:215], v[40:43]
	v_mfma_f32_16x16x32_bf16 v[28:31], v[130:133], v[220:223], v[28:31]
	v_mfma_f32_16x16x32_bf16 v[24:27], v[138:141], v[220:223], v[24:27]
	v_mfma_f32_16x16x32_bf16 v[12:15], v[130:133], v[228:231], v[12:15]
	v_mfma_f32_16x16x32_bf16 v[8:11], v[138:141], v[228:231], v[8:11]
	v_mfma_f32_16x16x32_bf16 v[60:63], v[134:137], v[208:211], v[60:63]
	v_mfma_f32_16x16x32_bf16 v[56:59], v[142:145], v[208:211], v[56:59]
	v_mfma_f32_16x16x32_bf16 v[44:47], v[134:137], v[216:219], v[44:47]
	v_mfma_f32_16x16x32_bf16 v[40:43], v[142:145], v[216:219], v[40:43]
	v_mfma_f32_16x16x32_bf16 v[28:31], v[134:137], v[224:227], v[28:31]
	v_mfma_f32_16x16x32_bf16 v[24:27], v[142:145], v[224:227], v[24:27]
	v_mfma_f32_16x16x32_bf16 v[12:15], v[134:137], v[232:235], v[12:15]
	v_mfma_f32_16x16x32_bf16 v[8:11], v[142:145], v[232:235], v[8:11]
	v_mfma_f32_16x16x32_bf16 v[52:55], v[146:149], v[204:207], v[52:55]
	v_mfma_f32_16x16x32_bf16 v[48:51], v[154:157], v[204:207], v[48:51]
	v_mfma_f32_16x16x32_bf16 v[36:39], v[146:149], v[212:215], v[36:39]
	v_mfma_f32_16x16x32_bf16 v[32:35], v[154:157], v[212:215], v[32:35]
	v_mfma_f32_16x16x32_bf16 v[20:23], v[146:149], v[220:223], v[20:23]
	v_mfma_f32_16x16x32_bf16 v[16:19], v[154:157], v[220:223], v[16:19]
	v_mfma_f32_16x16x32_bf16 v[4:7], v[146:149], v[228:231], v[4:7]
	v_mfma_f32_16x16x32_bf16 v[0:3], v[154:157], v[228:231], v[0:3]
	v_mfma_f32_16x16x32_bf16 v[52:55], v[150:153], v[208:211], v[52:55]
	v_mfma_f32_16x16x32_bf16 v[48:51], v[158:161], v[208:211], v[48:51]
	v_mfma_f32_16x16x32_bf16 v[36:39], v[150:153], v[216:219], v[36:39]
	v_mfma_f32_16x16x32_bf16 v[32:35], v[158:161], v[216:219], v[32:35]
	v_mfma_f32_16x16x32_bf16 v[20:23], v[150:153], v[224:227], v[20:23]
	v_mfma_f32_16x16x32_bf16 v[16:19], v[158:161], v[224:227], v[16:19]
	v_mfma_f32_16x16x32_bf16 v[4:7], v[150:153], v[232:235], v[4:7]
	v_mfma_f32_16x16x32_bf16 v[0:3], v[158:161], v[232:235], v[0:3]
	s_setprio 0
	s_barrier
	s_add_u32 s8, s8, 0x100
	s_addc_u32 s9, s9, 0
	s_add_u32 s16, s16, 0x100
	s_addc_u32 s84, s84, 0
	s_cmp_ge_i32 s85, s41
	s_mov_b32 s82, s85
	s_cbranch_scc0 .LBB0_746

.LBB0_950:
	s_add_i32 s87, s55, 2
	s_add_u32 s44, s80, 0x80
	s_addc_u32 s45, s81, 0
	s_add_i32 s58, 0, 0x10000
	s_cmp_eq_u32 s29, s55
	s_cselect_b32 s83, s11, s45
	s_cselect_b32 s82, s10, s44
	v_add_u32_e32 v128, s58, v185
	s_cselect_b32 s45, s79, s54
	s_cselect_b32 s44, s78, s16
	s_add_i32 s55, 0, 0x14000
	ds_read_b128 v[130:133], v128
	ds_read_b128 v[134:137], v128 offset:1024
	ds_read_b128 v[138:141], v128 offset:2048
	ds_read_b128 v[142:145], v128 offset:3072
	v_add_u32_e32 v128, s55, v185
	ds_read_b128 v[146:149], v128
	ds_read_b128 v[150:153], v128 offset:1024
	ds_read_b128 v[166:169], v128 offset:2048
	ds_read_b128 v[170:173], v128 offset:3072
	v_lshl_add_u64 v[220:221], s[80:81], 0, v[162:163]
	s_add_i32 m0, s40, 0xc000
	ds_read_b128 v[174:177], v187
	ds_read_b128 v[178:181], v187 offset:1024
	ds_read_b128 v[188:191], v187 offset:2048
	ds_read_b128 v[192:195], v187 offset:3072
	ds_read_b128 v[204:207], v187 offset:4096
	ds_read_b128 v[208:211], v187 offset:5120
	ds_read_b128 v[212:215], v187 offset:6144
	ds_read_b128 v[216:219], v187 offset:7168
	global_load_lds_dwordx4 v[220:221], off
	v_lshl_add_u64 v[220:221], s[80:81], 0, v[164:165]
	s_add_i32 m0, s40, 0xe000
	s_nop 0
	global_load_lds_dwordx4 v[220:221], off
	s_waitcnt vmcnt(8)
	s_waitcnt lgkmcnt(0)
	s_barrier
	s_setprio 1
	s_waitcnt lgkmcnt(0)
	v_mfma_f32_16x16x32_bf16 v[124:127], v[130:133], v[174:177], v[124:127]
	v_mfma_f32_16x16x32_bf16 v[120:123], v[138:141], v[174:177], v[120:123]
	v_mfma_f32_16x16x32_bf16 v[108:111], v[130:133], v[188:191], v[108:111]
	v_mfma_f32_16x16x32_bf16 v[104:107], v[138:141], v[188:191], v[104:107]
	v_mfma_f32_16x16x32_bf16 v[92:95], v[130:133], v[204:207], v[92:95]
	v_mfma_f32_16x16x32_bf16 v[88:91], v[138:141], v[204:207], v[88:91]
	v_mfma_f32_16x16x32_bf16 v[76:79], v[130:133], v[212:215], v[76:79]
	v_mfma_f32_16x16x32_bf16 v[72:75], v[138:141], v[212:215], v[72:75]
	v_mfma_f32_16x16x32_bf16 v[124:127], v[134:137], v[178:181], v[124:127]
	v_mfma_f32_16x16x32_bf16 v[120:123], v[142:145], v[178:181], v[120:123]
	v_mfma_f32_16x16x32_bf16 v[108:111], v[134:137], v[192:195], v[108:111]
	v_mfma_f32_16x16x32_bf16 v[104:107], v[142:145], v[192:195], v[104:107]
	v_mfma_f32_16x16x32_bf16 v[92:95], v[134:137], v[208:211], v[92:95]
	v_mfma_f32_16x16x32_bf16 v[88:91], v[142:145], v[208:211], v[88:91]
	v_mfma_f32_16x16x32_bf16 v[76:79], v[134:137], v[216:219], v[76:79]
	v_mfma_f32_16x16x32_bf16 v[72:75], v[142:145], v[216:219], v[72:75]
	v_mfma_f32_16x16x32_bf16 v[116:119], v[146:149], v[174:177], v[116:119]
	v_mfma_f32_16x16x32_bf16 v[112:115], v[166:169], v[174:177], v[112:115]
	v_mfma_f32_16x16x32_bf16 v[100:103], v[146:149], v[188:191], v[100:103]
	v_mfma_f32_16x16x32_bf16 v[96:99], v[166:169], v[188:191], v[96:99]
	v_mfma_f32_16x16x32_bf16 v[84:87], v[146:149], v[204:207], v[84:87]
	v_mfma_f32_16x16x32_bf16 v[80:83], v[166:169], v[204:207], v[80:83]
	v_mfma_f32_16x16x32_bf16 v[68:71], v[146:149], v[212:215], v[68:71]
	v_mfma_f32_16x16x32_bf16 v[64:67], v[166:169], v[212:215], v[64:67]
	v_mfma_f32_16x16x32_bf16 v[116:119], v[150:153], v[178:181], v[116:119]
	v_mfma_f32_16x16x32_bf16 v[112:115], v[170:173], v[178:181], v[112:115]
	v_mfma_f32_16x16x32_bf16 v[100:103], v[150:153], v[192:195], v[100:103]
	v_mfma_f32_16x16x32_bf16 v[96:99], v[170:173], v[192:195], v[96:99]
	v_mfma_f32_16x16x32_bf16 v[84:87], v[150:153], v[208:211], v[84:87]
	v_mfma_f32_16x16x32_bf16 v[80:83], v[170:173], v[208:211], v[80:83]
	v_mfma_f32_16x16x32_bf16 v[68:71], v[150:153], v[216:219], v[68:71]
	v_mfma_f32_16x16x32_bf16 v[64:67], v[170:173], v[216:219], v[64:67]
	s_setprio 0
	s_barrier
	s_add_i32 s58, s58, s86
	v_lshl_add_u64 v[220:221], s[44:45], 0, v[158:159]
	s_mov_b32 m0, s58
	ds_read_b128 v[174:177], v187 offset:16384
	ds_read_b128 v[178:181], v187 offset:17408
	ds_read_b128 v[188:191], v187 offset:18432
	ds_read_b128 v[192:195], v187 offset:19456
	ds_read_b128 v[204:207], v187 offset:20480
	ds_read_b128 v[208:211], v187 offset:21504
	ds_read_b128 v[212:215], v187 offset:22528
	ds_read_b128 v[216:219], v187 offset:23552
	global_load_lds_dwordx4 v[220:221], off
	s_add_i32 m0, s58, 0x2000
	v_lshl_add_u64 v[222:223], s[44:45], 0, v[154:155]
	s_add_u32 s44, s44, s64
	s_addc_u32 s45, s45, s65
	s_add_i32 s55, s55, s86
	global_load_lds_dwordx4 v[222:223], off
	v_lshl_add_u64 v[224:225], s[44:45], 0, v[158:159]
	s_mov_b32 m0, s55
	v_lshl_add_u64 v[226:227], s[44:45], 0, v[154:155]
	global_load_lds_dwordx4 v[224:225], off
	s_add_i32 m0, s55, 0x2000
	v_lshl_add_u64 v[228:229], s[82:83], 0, v[160:161]
	global_load_lds_dwordx4 v[226:227], off
	s_mov_b32 m0, s40
	v_lshl_add_u64 v[230:231], s[82:83], 0, v[156:157]
	global_load_lds_dwordx4 v[228:229], off
	s_mov_b32 m0, s12
	s_nop 0
	global_load_lds_dwordx4 v[230:231], off
	s_waitcnt vmcnt(8)
	s_waitcnt lgkmcnt(0)
	s_barrier
	s_setprio 1
	s_waitcnt lgkmcnt(0)
	v_mfma_f32_16x16x32_bf16 v[60:63], v[130:133], v[174:177], v[60:63]
	v_mfma_f32_16x16x32_bf16 v[56:59], v[138:141], v[174:177], v[56:59]
	v_mfma_f32_16x16x32_bf16 v[44:47], v[130:133], v[188:191], v[44:47]
	v_mfma_f32_16x16x32_bf16 v[40:43], v[138:141], v[188:191], v[40:43]
	v_mfma_f32_16x16x32_bf16 v[28:31], v[130:133], v[204:207], v[28:31]
	v_mfma_f32_16x16x32_bf16 v[24:27], v[138:141], v[204:207], v[24:27]
	v_mfma_f32_16x16x32_bf16 v[12:15], v[130:133], v[212:215], v[12:15]
	v_mfma_f32_16x16x32_bf16 v[8:11], v[138:141], v[212:215], v[8:11]
	v_mfma_f32_16x16x32_bf16 v[60:63], v[134:137], v[178:181], v[60:63]
	v_mfma_f32_16x16x32_bf16 v[56:59], v[142:145], v[178:181], v[56:59]
	v_mfma_f32_16x16x32_bf16 v[44:47], v[134:137], v[192:195], v[44:47]
	v_mfma_f32_16x16x32_bf16 v[40:43], v[142:145], v[192:195], v[40:43]
	v_mfma_f32_16x16x32_bf16 v[28:31], v[134:137], v[208:211], v[28:31]
	v_mfma_f32_16x16x32_bf16 v[24:27], v[142:145], v[208:211], v[24:27]
	v_mfma_f32_16x16x32_bf16 v[12:15], v[134:137], v[216:219], v[12:15]
	v_mfma_f32_16x16x32_bf16 v[8:11], v[142:145], v[216:219], v[8:11]
	v_mfma_f32_16x16x32_bf16 v[52:55], v[146:149], v[174:177], v[52:55]
	v_mfma_f32_16x16x32_bf16 v[48:51], v[166:169], v[174:177], v[48:51]
	v_mfma_f32_16x16x32_bf16 v[36:39], v[146:149], v[188:191], v[36:39]
	v_mfma_f32_16x16x32_bf16 v[32:35], v[166:169], v[188:191], v[32:35]
	v_mfma_f32_16x16x32_bf16 v[20:23], v[146:149], v[204:207], v[20:23]
	v_mfma_f32_16x16x32_bf16 v[16:19], v[166:169], v[204:207], v[16:19]
	v_mfma_f32_16x16x32_bf16 v[4:7], v[146:149], v[212:215], v[4:7]
	v_mfma_f32_16x16x32_bf16 v[0:3], v[166:169], v[212:215], v[0:3]
	v_mfma_f32_16x16x32_bf16 v[52:55], v[150:153], v[178:181], v[52:55]
	v_mfma_f32_16x16x32_bf16 v[48:51], v[170:173], v[178:181], v[48:51]
	v_mfma_f32_16x16x32_bf16 v[36:39], v[150:153], v[192:195], v[36:39]
	v_mfma_f32_16x16x32_bf16 v[32:35], v[170:173], v[192:195], v[32:35]
	v_mfma_f32_16x16x32_bf16 v[20:23], v[150:153], v[208:211], v[20:23]
	v_mfma_f32_16x16x32_bf16 v[16:19], v[170:173], v[208:211], v[16:19]
	v_mfma_f32_16x16x32_bf16 v[4:7], v[150:153], v[216:219], v[4:7]
	v_mfma_f32_16x16x32_bf16 v[0:3], v[170:173], v[216:219], v[0:3]
	s_setprio 0
	s_barrier
	s_add_i32 s55, 0, 0x18000
	v_add_u32_e32 v128, s55, v185
	s_add_i32 s58, 0, 0x1c000
	ds_read_b128 v[130:133], v128
	ds_read_b128 v[134:137], v128 offset:1024
	ds_read_b128 v[138:141], v128 offset:2048
	ds_read_b128 v[142:145], v128 offset:3072
	v_add_u32_e32 v128, s58, v185
	ds_read_b128 v[146:149], v128
	ds_read_b128 v[150:153], v128 offset:1024
	ds_read_b128 v[166:169], v128 offset:2048
	ds_read_b128 v[170:173], v128 offset:3072
	s_add_u32 s44, s82, s64
	s_addc_u32 s45, s83, s65
	s_mov_b32 m0, s4
	v_lshl_add_u64 v[232:233], s[44:45], 0, v[160:161]
	ds_read_b128 v[174:177], v187 offset:32768
	ds_read_b128 v[178:181], v187 offset:33792
	ds_read_b128 v[188:191], v187 offset:34816
	ds_read_b128 v[192:195], v187 offset:35840
	ds_read_b128 v[204:207], v187 offset:36864
	ds_read_b128 v[208:211], v187 offset:37888
	ds_read_b128 v[212:215], v187 offset:38912
	ds_read_b128 v[216:219], v187 offset:39936
	global_load_lds_dwordx4 v[232:233], off
	v_lshl_add_u64 v[232:233], s[44:45], 0, v[156:157]
	s_mov_b32 m0, s5
	s_nop 0
	global_load_lds_dwordx4 v[232:233], off
	s_waitcnt vmcnt(8)
	s_waitcnt lgkmcnt(0)
	s_barrier
	s_setprio 1
	s_waitcnt lgkmcnt(0)
	v_mfma_f32_16x16x32_bf16 v[124:127], v[130:133], v[174:177], v[124:127]
	v_mfma_f32_16x16x32_bf16 v[120:123], v[138:141], v[174:177], v[120:123]
	v_mfma_f32_16x16x32_bf16 v[108:111], v[130:133], v[188:191], v[108:111]
	v_mfma_f32_16x16x32_bf16 v[104:107], v[138:141], v[188:191], v[104:107]
	v_mfma_f32_16x16x32_bf16 v[92:95], v[130:133], v[204:207], v[92:95]
	v_mfma_f32_16x16x32_bf16 v[88:91], v[138:141], v[204:207], v[88:91]
	v_mfma_f32_16x16x32_bf16 v[76:79], v[130:133], v[212:215], v[76:79]
	v_mfma_f32_16x16x32_bf16 v[72:75], v[138:141], v[212:215], v[72:75]
	v_mfma_f32_16x16x32_bf16 v[124:127], v[134:137], v[178:181], v[124:127]
	v_mfma_f32_16x16x32_bf16 v[120:123], v[142:145], v[178:181], v[120:123]
	v_mfma_f32_16x16x32_bf16 v[108:111], v[134:137], v[192:195], v[108:111]
	v_mfma_f32_16x16x32_bf16 v[104:107], v[142:145], v[192:195], v[104:107]
	v_mfma_f32_16x16x32_bf16 v[92:95], v[134:137], v[208:211], v[92:95]
	v_mfma_f32_16x16x32_bf16 v[88:91], v[142:145], v[208:211], v[88:91]
	v_mfma_f32_16x16x32_bf16 v[76:79], v[134:137], v[216:219], v[76:79]
	v_mfma_f32_16x16x32_bf16 v[72:75], v[142:145], v[216:219], v[72:75]
	v_mfma_f32_16x16x32_bf16 v[116:119], v[146:149], v[174:177], v[116:119]
	v_mfma_f32_16x16x32_bf16 v[112:115], v[166:169], v[174:177], v[112:115]
	v_mfma_f32_16x16x32_bf16 v[100:103], v[146:149], v[188:191], v[100:103]
	v_mfma_f32_16x16x32_bf16 v[96:99], v[166:169], v[188:191], v[96:99]
	v_mfma_f32_16x16x32_bf16 v[84:87], v[146:149], v[204:207], v[84:87]
	v_mfma_f32_16x16x32_bf16 v[80:83], v[166:169], v[204:207], v[80:83]
	v_mfma_f32_16x16x32_bf16 v[68:71], v[146:149], v[212:215], v[68:71]
	v_mfma_f32_16x16x32_bf16 v[64:67], v[166:169], v[212:215], v[64:67]
	v_mfma_f32_16x16x32_bf16 v[116:119], v[150:153], v[178:181], v[116:119]
	v_mfma_f32_16x16x32_bf16 v[112:115], v[170:173], v[178:181], v[112:115]
	v_mfma_f32_16x16x32_bf16 v[100:103], v[150:153], v[192:195], v[100:103]
	v_mfma_f32_16x16x32_bf16 v[96:99], v[170:173], v[192:195], v[96:99]
	v_mfma_f32_16x16x32_bf16 v[84:87], v[150:153], v[208:211], v[84:87]
	v_mfma_f32_16x16x32_bf16 v[80:83], v[170:173], v[208:211], v[80:83]
	v_mfma_f32_16x16x32_bf16 v[68:71], v[150:153], v[216:219], v[68:71]
	v_mfma_f32_16x16x32_bf16 v[64:67], v[170:173], v[216:219], v[64:67]
	s_setprio 0
	s_barrier
	s_add_i32 s44, s55, s86
	v_lshl_add_u64 v[220:221], v[220:221], 0, s[52:53]
	s_mov_b32 m0, s44
	ds_read_b128 v[174:177], v187 offset:49152
	ds_read_b128 v[178:181], v187 offset:50176
	ds_read_b128 v[188:191], v187 offset:51200
	ds_read_b128 v[192:195], v187 offset:52224
	ds_read_b128 v[204:207], v187 offset:53248
	ds_read_b128 v[208:211], v187 offset:54272
	ds_read_b128 v[212:215], v187 offset:55296
	ds_read_b128 v[216:219], v187 offset:56320
	global_load_lds_dwordx4 v[220:221], off
	v_lshl_add_u64 v[220:221], v[222:223], 0, s[52:53]
	s_add_i32 m0, s44, 0x2000
	s_add_i32 s44, s58, s86
	global_load_lds_dwordx4 v[220:221], off
	v_lshl_add_u64 v[220:221], v[224:225], 0, s[52:53]
	s_mov_b32 m0, s44
	s_nop 0
	global_load_lds_dwordx4 v[220:221], off
	v_lshl_add_u64 v[220:221], v[226:227], 0, s[52:53]
	s_add_i32 m0, s44, 0x2000
	s_nop 0
	global_load_lds_dwordx4 v[220:221], off
	v_lshl_add_u64 v[220:221], v[228:229], 0, s[52:53]
	s_mov_b32 m0, s22
	s_nop 0
	global_load_lds_dwordx4 v[220:221], off
	v_lshl_add_u64 v[220:221], v[230:231], 0, s[52:53]
	s_mov_b32 m0, s23
	s_nop 0
	global_load_lds_dwordx4 v[220:221], off
	s_waitcnt vmcnt(8)
	s_waitcnt lgkmcnt(0)
	s_barrier
	s_setprio 1
	s_waitcnt lgkmcnt(0)
	v_mfma_f32_16x16x32_bf16 v[60:63], v[130:133], v[174:177], v[60:63]
	v_mfma_f32_16x16x32_bf16 v[56:59], v[138:141], v[174:177], v[56:59]
	v_mfma_f32_16x16x32_bf16 v[44:47], v[130:133], v[188:191], v[44:47]
	v_mfma_f32_16x16x32_bf16 v[40:43], v[138:141], v[188:191], v[40:43]
	v_mfma_f32_16x16x32_bf16 v[28:31], v[130:133], v[204:207], v[28:31]
	v_mfma_f32_16x16x32_bf16 v[24:27], v[138:141], v[204:207], v[24:27]
	v_mfma_f32_16x16x32_bf16 v[12:15], v[130:133], v[212:215], v[12:15]
	v_mfma_f32_16x16x32_bf16 v[8:11], v[138:141], v[212:215], v[8:11]
	v_mfma_f32_16x16x32_bf16 v[60:63], v[134:137], v[178:181], v[60:63]
	v_mfma_f32_16x16x32_bf16 v[56:59], v[142:145], v[178:181], v[56:59]
	v_mfma_f32_16x16x32_bf16 v[44:47], v[134:137], v[192:195], v[44:47]
	v_mfma_f32_16x16x32_bf16 v[40:43], v[142:145], v[192:195], v[40:43]
	v_mfma_f32_16x16x32_bf16 v[28:31], v[134:137], v[208:211], v[28:31]
	v_mfma_f32_16x16x32_bf16 v[24:27], v[142:145], v[208:211], v[24:27]
	v_mfma_f32_16x16x32_bf16 v[12:15], v[134:137], v[216:219], v[12:15]
	v_mfma_f32_16x16x32_bf16 v[8:11], v[142:145], v[216:219], v[8:11]
	v_mfma_f32_16x16x32_bf16 v[52:55], v[146:149], v[174:177], v[52:55]
	v_mfma_f32_16x16x32_bf16 v[48:51], v[166:169], v[174:177], v[48:51]
	v_mfma_f32_16x16x32_bf16 v[36:39], v[146:149], v[188:191], v[36:39]
	v_mfma_f32_16x16x32_bf16 v[32:35], v[166:169], v[188:191], v[32:35]
	v_mfma_f32_16x16x32_bf16 v[20:23], v[146:149], v[204:207], v[20:23]
	v_mfma_f32_16x16x32_bf16 v[16:19], v[166:169], v[204:207], v[16:19]
	v_mfma_f32_16x16x32_bf16 v[4:7], v[146:149], v[212:215], v[4:7]
	v_mfma_f32_16x16x32_bf16 v[0:3], v[166:169], v[212:215], v[0:3]
	v_mfma_f32_16x16x32_bf16 v[52:55], v[150:153], v[178:181], v[52:55]
	v_mfma_f32_16x16x32_bf16 v[48:51], v[170:173], v[178:181], v[48:51]
	v_mfma_f32_16x16x32_bf16 v[36:39], v[150:153], v[192:195], v[36:39]
	v_mfma_f32_16x16x32_bf16 v[32:35], v[170:173], v[192:195], v[32:35]
	v_mfma_f32_16x16x32_bf16 v[20:23], v[150:153], v[208:211], v[20:23]
	v_mfma_f32_16x16x32_bf16 v[16:19], v[170:173], v[208:211], v[16:19]
	v_mfma_f32_16x16x32_bf16 v[4:7], v[150:153], v[216:219], v[4:7]
	v_mfma_f32_16x16x32_bf16 v[0:3], v[170:173], v[216:219], v[0:3]
	s_setprio 0
	s_barrier
	s_add_u32 s80, s80, 0x100
	s_addc_u32 s81, s81, 0
	s_add_u32 s16, s16, 0x100
	s_addc_u32 s54, s54, 0
	s_cmp_ge_i32 s87, s13
	s_mov_b32 s55, s87
	s_cbranch_scc0 .LBB0_950

.LBB0_1042:
	s_add_i32 s83, s78, 2
	s_add_u32 s44, s76, 0x80
	s_addc_u32 s45, s77, 0
	s_add_i32 s58, 0, 0x10000
	s_cmp_eq_u32 s54, s78
	s_cselect_b32 s79, s9, s45
	s_cselect_b32 s78, s8, s44
	s_cselect_b32 s45, s75, s82
	s_cselect_b32 s44, s74, s16
	s_add_i32 s84, 0, 0x14000
	v_add_u32_e32 v158, s58, v146
	v_add_u32_e32 v174, s84, v146
	ds_read_b128 v[142:145], v158
	ds_read_b128 v[150:153], v158 offset:1024
	ds_read_b128 v[154:157], v158 offset:2048
	ds_read_b128 v[158:161], v158 offset:3072
	ds_read_b128 v[162:165], v174
	ds_read_b128 v[166:169], v174 offset:1024
	ds_read_b128 v[170:173], v174 offset:2048
	ds_read_b128 v[174:177], v174 offset:3072
	v_lshl_add_u64 v[220:221], s[76:77], 0, v[138:139]
	s_add_i32 m0, s23, 0xc000
	ds_read_b128 v[178:181], v149
	ds_read_b128 v[184:187], v149 offset:1024
	ds_read_b128 v[188:191], v149 offset:2048
	ds_read_b128 v[192:195], v149 offset:3072
	ds_read_b128 v[204:207], v149 offset:4096
	ds_read_b128 v[208:211], v149 offset:5120
	ds_read_b128 v[212:215], v149 offset:6144
	ds_read_b128 v[216:219], v149 offset:7168
	global_load_lds_dwordx4 v[220:221], off
	v_lshl_add_u64 v[220:221], s[76:77], 0, v[140:141]
	s_add_i32 m0, s23, 0xe000
	s_nop 0
	global_load_lds_dwordx4 v[220:221], off
	s_waitcnt vmcnt(8)
	s_waitcnt lgkmcnt(0)
	s_barrier
	s_setprio 1
	s_waitcnt lgkmcnt(0)
	v_mfma_f32_16x16x32_bf16 v[120:123], v[142:145], v[178:181], v[120:123]
	v_mfma_f32_16x16x32_bf16 v[116:119], v[154:157], v[178:181], v[116:119]
	v_mfma_f32_16x16x32_bf16 v[108:111], v[142:145], v[188:191], v[108:111]
	v_mfma_f32_16x16x32_bf16 v[100:103], v[154:157], v[188:191], v[100:103]
	v_mfma_f32_16x16x32_bf16 v[92:95], v[142:145], v[204:207], v[92:95]
	v_mfma_f32_16x16x32_bf16 v[84:87], v[154:157], v[204:207], v[84:87]
	v_mfma_f32_16x16x32_bf16 v[76:79], v[142:145], v[212:215], v[76:79]
	v_mfma_f32_16x16x32_bf16 v[68:71], v[154:157], v[212:215], v[68:71]
	v_mfma_f32_16x16x32_bf16 v[120:123], v[150:153], v[184:187], v[120:123]
	v_mfma_f32_16x16x32_bf16 v[116:119], v[158:161], v[184:187], v[116:119]
	v_mfma_f32_16x16x32_bf16 v[108:111], v[150:153], v[192:195], v[108:111]
	v_mfma_f32_16x16x32_bf16 v[100:103], v[158:161], v[192:195], v[100:103]
	v_mfma_f32_16x16x32_bf16 v[92:95], v[150:153], v[208:211], v[92:95]
	v_mfma_f32_16x16x32_bf16 v[84:87], v[158:161], v[208:211], v[84:87]
	v_mfma_f32_16x16x32_bf16 v[76:79], v[150:153], v[216:219], v[76:79]
	v_mfma_f32_16x16x32_bf16 v[68:71], v[158:161], v[216:219], v[68:71]
	v_mfma_f32_16x16x32_bf16 v[124:127], v[162:165], v[178:181], v[124:127]
	v_mfma_f32_16x16x32_bf16 v[112:115], v[170:173], v[178:181], v[112:115]
	v_mfma_f32_16x16x32_bf16 v[104:107], v[162:165], v[188:191], v[104:107]
	v_mfma_f32_16x16x32_bf16 v[96:99], v[170:173], v[188:191], v[96:99]
	v_mfma_f32_16x16x32_bf16 v[88:91], v[162:165], v[204:207], v[88:91]
	v_mfma_f32_16x16x32_bf16 v[80:83], v[170:173], v[204:207], v[80:83]
	v_mfma_f32_16x16x32_bf16 v[72:75], v[162:165], v[212:215], v[72:75]
	v_mfma_f32_16x16x32_bf16 v[64:67], v[170:173], v[212:215], v[64:67]
	v_mfma_f32_16x16x32_bf16 v[124:127], v[166:169], v[184:187], v[124:127]
	v_mfma_f32_16x16x32_bf16 v[112:115], v[174:177], v[184:187], v[112:115]
	v_mfma_f32_16x16x32_bf16 v[104:107], v[166:169], v[192:195], v[104:107]
	v_mfma_f32_16x16x32_bf16 v[96:99], v[174:177], v[192:195], v[96:99]
	v_mfma_f32_16x16x32_bf16 v[88:91], v[166:169], v[208:211], v[88:91]
	v_mfma_f32_16x16x32_bf16 v[80:83], v[174:177], v[208:211], v[80:83]
	v_mfma_f32_16x16x32_bf16 v[72:75], v[166:169], v[216:219], v[72:75]
	v_mfma_f32_16x16x32_bf16 v[64:67], v[174:177], v[216:219], v[64:67]
	s_setprio 0
	s_barrier
	s_add_i32 s58, s58, s22
	v_lshl_add_u64 v[220:221], s[44:45], 0, v[128:129]
	s_mov_b32 m0, s58
	ds_read_b128 v[178:181], v149 offset:16384
	ds_read_b128 v[184:187], v149 offset:17408
	ds_read_b128 v[188:191], v149 offset:18432
	ds_read_b128 v[192:195], v149 offset:19456
	ds_read_b128 v[204:207], v149 offset:20480
	ds_read_b128 v[208:211], v149 offset:21504
	ds_read_b128 v[212:215], v149 offset:22528
	ds_read_b128 v[216:219], v149 offset:23552
	global_load_lds_dwordx4 v[220:221], off
	s_add_i32 m0, s58, 0x2000
	v_lshl_add_u64 v[222:223], s[44:45], 0, v[130:131]
	s_add_u32 s44, s44, s10
	s_addc_u32 s45, s45, s11
	s_add_i32 s58, s84, s22
	global_load_lds_dwordx4 v[222:223], off
	v_lshl_add_u64 v[224:225], s[44:45], 0, v[128:129]
	s_mov_b32 m0, s58
	v_lshl_add_u64 v[226:227], s[44:45], 0, v[130:131]
	global_load_lds_dwordx4 v[224:225], off
	s_add_i32 m0, s58, 0x2000
	v_lshl_add_u64 v[228:229], s[78:79], 0, v[134:135]
	global_load_lds_dwordx4 v[226:227], off
	s_mov_b32 m0, s23
	v_lshl_add_u64 v[230:231], s[78:79], 0, v[132:133]
	global_load_lds_dwordx4 v[228:229], off
	s_mov_b32 m0, s29
	s_nop 0
	global_load_lds_dwordx4 v[230:231], off
	s_waitcnt vmcnt(8)
	s_waitcnt lgkmcnt(0)
	s_barrier
	s_setprio 1
	s_waitcnt lgkmcnt(0)
	v_mfma_f32_16x16x32_bf16 v[60:63], v[142:145], v[178:181], v[60:63]
	v_mfma_f32_16x16x32_bf16 v[52:55], v[154:157], v[178:181], v[52:55]
	v_mfma_f32_16x16x32_bf16 v[44:47], v[142:145], v[188:191], v[44:47]
	v_mfma_f32_16x16x32_bf16 v[36:39], v[154:157], v[188:191], v[36:39]
	v_mfma_f32_16x16x32_bf16 v[28:31], v[142:145], v[204:207], v[28:31]
	v_mfma_f32_16x16x32_bf16 v[20:23], v[154:157], v[204:207], v[20:23]
	v_mfma_f32_16x16x32_bf16 v[12:15], v[142:145], v[212:215], v[12:15]
	v_mfma_f32_16x16x32_bf16 v[4:7], v[154:157], v[212:215], v[4:7]
	v_mfma_f32_16x16x32_bf16 v[60:63], v[150:153], v[184:187], v[60:63]
	v_mfma_f32_16x16x32_bf16 v[52:55], v[158:161], v[184:187], v[52:55]
	v_mfma_f32_16x16x32_bf16 v[44:47], v[150:153], v[192:195], v[44:47]
	v_mfma_f32_16x16x32_bf16 v[36:39], v[158:161], v[192:195], v[36:39]
	v_mfma_f32_16x16x32_bf16 v[28:31], v[150:153], v[208:211], v[28:31]
	v_mfma_f32_16x16x32_bf16 v[20:23], v[158:161], v[208:211], v[20:23]
	v_mfma_f32_16x16x32_bf16 v[12:15], v[150:153], v[216:219], v[12:15]
	v_mfma_f32_16x16x32_bf16 v[4:7], v[158:161], v[216:219], v[4:7]
	v_mfma_f32_16x16x32_bf16 v[56:59], v[162:165], v[178:181], v[56:59]
	v_mfma_f32_16x16x32_bf16 v[48:51], v[170:173], v[178:181], v[48:51]
	v_mfma_f32_16x16x32_bf16 v[40:43], v[162:165], v[188:191], v[40:43]
	v_mfma_f32_16x16x32_bf16 v[32:35], v[170:173], v[188:191], v[32:35]
	v_mfma_f32_16x16x32_bf16 v[24:27], v[162:165], v[204:207], v[24:27]
	v_mfma_f32_16x16x32_bf16 v[16:19], v[170:173], v[204:207], v[16:19]
	v_mfma_f32_16x16x32_bf16 v[8:11], v[162:165], v[212:215], v[8:11]
	v_mfma_f32_16x16x32_bf16 v[0:3], v[170:173], v[212:215], v[0:3]
	v_mfma_f32_16x16x32_bf16 v[56:59], v[166:169], v[184:187], v[56:59]
	v_mfma_f32_16x16x32_bf16 v[48:51], v[174:177], v[184:187], v[48:51]
	v_mfma_f32_16x16x32_bf16 v[40:43], v[166:169], v[192:195], v[40:43]
	v_mfma_f32_16x16x32_bf16 v[32:35], v[174:177], v[192:195], v[32:35]
	v_mfma_f32_16x16x32_bf16 v[24:27], v[166:169], v[208:211], v[24:27]
	v_mfma_f32_16x16x32_bf16 v[16:19], v[174:177], v[208:211], v[16:19]
	v_mfma_f32_16x16x32_bf16 v[8:11], v[166:169], v[216:219], v[8:11]
	v_mfma_f32_16x16x32_bf16 v[0:3], v[174:177], v[216:219], v[0:3]
	s_setprio 0
	s_barrier
	s_add_i32 s58, 0, 0x18000
	s_add_i32 s84, 0, 0x1c000
	v_add_u32_e32 v158, s58, v146
	v_add_u32_e32 v174, s84, v146
	ds_read_b128 v[142:145], v158
	ds_read_b128 v[150:153], v158 offset:1024
	ds_read_b128 v[154:157], v158 offset:2048
	ds_read_b128 v[158:161], v158 offset:3072
	ds_read_b128 v[162:165], v174
	ds_read_b128 v[166:169], v174 offset:1024
	ds_read_b128 v[170:173], v174 offset:2048
	ds_read_b128 v[174:177], v174 offset:3072
	s_add_u32 s44, s78, s10
	s_addc_u32 s45, s79, s11
	s_mov_b32 m0, s39
	v_lshl_add_u64 v[232:233], s[44:45], 0, v[134:135]
	ds_read_b128 v[178:181], v149 offset:32768
	ds_read_b128 v[184:187], v149 offset:33792
	ds_read_b128 v[188:191], v149 offset:34816
	ds_read_b128 v[192:195], v149 offset:35840
	ds_read_b128 v[204:207], v149 offset:36864
	ds_read_b128 v[208:211], v149 offset:37888
	ds_read_b128 v[212:215], v149 offset:38912
	ds_read_b128 v[216:219], v149 offset:39936
	global_load_lds_dwordx4 v[232:233], off
	v_lshl_add_u64 v[232:233], s[44:45], 0, v[132:133]
	s_mov_b32 m0, s40
	s_nop 0
	global_load_lds_dwordx4 v[232:233], off
	s_waitcnt vmcnt(8)
	s_waitcnt lgkmcnt(0)
	s_barrier
	s_setprio 1
	s_waitcnt lgkmcnt(0)
	v_mfma_f32_16x16x32_bf16 v[120:123], v[142:145], v[178:181], v[120:123]
	v_mfma_f32_16x16x32_bf16 v[116:119], v[154:157], v[178:181], v[116:119]
	v_mfma_f32_16x16x32_bf16 v[108:111], v[142:145], v[188:191], v[108:111]
	v_mfma_f32_16x16x32_bf16 v[100:103], v[154:157], v[188:191], v[100:103]
	v_mfma_f32_16x16x32_bf16 v[92:95], v[142:145], v[204:207], v[92:95]
	v_mfma_f32_16x16x32_bf16 v[84:87], v[154:157], v[204:207], v[84:87]
	v_mfma_f32_16x16x32_bf16 v[76:79], v[142:145], v[212:215], v[76:79]
	v_mfma_f32_16x16x32_bf16 v[68:71], v[154:157], v[212:215], v[68:71]
	v_mfma_f32_16x16x32_bf16 v[120:123], v[150:153], v[184:187], v[120:123]
	v_mfma_f32_16x16x32_bf16 v[116:119], v[158:161], v[184:187], v[116:119]
	v_mfma_f32_16x16x32_bf16 v[108:111], v[150:153], v[192:195], v[108:111]
	v_mfma_f32_16x16x32_bf16 v[100:103], v[158:161], v[192:195], v[100:103]
	v_mfma_f32_16x16x32_bf16 v[92:95], v[150:153], v[208:211], v[92:95]
	v_mfma_f32_16x16x32_bf16 v[84:87], v[158:161], v[208:211], v[84:87]
	v_mfma_f32_16x16x32_bf16 v[76:79], v[150:153], v[216:219], v[76:79]
	v_mfma_f32_16x16x32_bf16 v[68:71], v[158:161], v[216:219], v[68:71]
	v_mfma_f32_16x16x32_bf16 v[124:127], v[162:165], v[178:181], v[124:127]
	v_mfma_f32_16x16x32_bf16 v[112:115], v[170:173], v[178:181], v[112:115]
	v_mfma_f32_16x16x32_bf16 v[104:107], v[162:165], v[188:191], v[104:107]
	v_mfma_f32_16x16x32_bf16 v[96:99], v[170:173], v[188:191], v[96:99]
	v_mfma_f32_16x16x32_bf16 v[88:91], v[162:165], v[204:207], v[88:91]
	v_mfma_f32_16x16x32_bf16 v[80:83], v[170:173], v[204:207], v[80:83]
	v_mfma_f32_16x16x32_bf16 v[72:75], v[162:165], v[212:215], v[72:75]
	v_mfma_f32_16x16x32_bf16 v[64:67], v[170:173], v[212:215], v[64:67]
	v_mfma_f32_16x16x32_bf16 v[124:127], v[166:169], v[184:187], v[124:127]
	v_mfma_f32_16x16x32_bf16 v[112:115], v[174:177], v[184:187], v[112:115]
	v_mfma_f32_16x16x32_bf16 v[104:107], v[166:169], v[192:195], v[104:107]
	v_mfma_f32_16x16x32_bf16 v[96:99], v[174:177], v[192:195], v[96:99]
	v_mfma_f32_16x16x32_bf16 v[88:91], v[166:169], v[208:211], v[88:91]
	v_mfma_f32_16x16x32_bf16 v[80:83], v[174:177], v[208:211], v[80:83]
	v_mfma_f32_16x16x32_bf16 v[72:75], v[166:169], v[216:219], v[72:75]
	v_mfma_f32_16x16x32_bf16 v[64:67], v[174:177], v[216:219], v[64:67]
	s_setprio 0
	s_barrier
	s_add_i32 s44, s58, s22
	v_lshl_add_u64 v[220:221], v[220:221], 0, s[52:53]
	s_mov_b32 m0, s44
	ds_read_b128 v[178:181], v149 offset:49152
	ds_read_b128 v[184:187], v149 offset:50176
	ds_read_b128 v[188:191], v149 offset:51200
	ds_read_b128 v[192:195], v149 offset:52224
	ds_read_b128 v[204:207], v149 offset:53248
	ds_read_b128 v[208:211], v149 offset:54272
	ds_read_b128 v[212:215], v149 offset:55296
	ds_read_b128 v[216:219], v149 offset:56320
	global_load_lds_dwordx4 v[220:221], off
	v_lshl_add_u64 v[220:221], v[222:223], 0, s[52:53]
	s_add_i32 m0, s44, 0x2000
	s_add_i32 s44, s84, s22
	global_load_lds_dwordx4 v[220:221], off
	v_lshl_add_u64 v[220:221], v[224:225], 0, s[52:53]
	s_mov_b32 m0, s44
	s_nop 0
	global_load_lds_dwordx4 v[220:221], off
	v_lshl_add_u64 v[220:221], v[226:227], 0, s[52:53]
	s_add_i32 m0, s44, 0x2000
	s_nop 0
	global_load_lds_dwordx4 v[220:221], off
	v_lshl_add_u64 v[220:221], v[228:229], 0, s[52:53]
	s_mov_b32 m0, s41
	s_nop 0
	global_load_lds_dwordx4 v[220:221], off
	v_lshl_add_u64 v[220:221], v[230:231], 0, s[52:53]
	s_mov_b32 m0, s46
	s_nop 0
	global_load_lds_dwordx4 v[220:221], off
	s_waitcnt vmcnt(8)
	s_waitcnt lgkmcnt(0)
	s_barrier
	s_setprio 1
	s_waitcnt lgkmcnt(0)
	v_mfma_f32_16x16x32_bf16 v[60:63], v[142:145], v[178:181], v[60:63]
	v_mfma_f32_16x16x32_bf16 v[52:55], v[154:157], v[178:181], v[52:55]
	v_mfma_f32_16x16x32_bf16 v[44:47], v[142:145], v[188:191], v[44:47]
	v_mfma_f32_16x16x32_bf16 v[36:39], v[154:157], v[188:191], v[36:39]
	v_mfma_f32_16x16x32_bf16 v[28:31], v[142:145], v[204:207], v[28:31]
	v_mfma_f32_16x16x32_bf16 v[20:23], v[154:157], v[204:207], v[20:23]
	v_mfma_f32_16x16x32_bf16 v[12:15], v[142:145], v[212:215], v[12:15]
	v_mfma_f32_16x16x32_bf16 v[4:7], v[154:157], v[212:215], v[4:7]
	v_mfma_f32_16x16x32_bf16 v[60:63], v[150:153], v[184:187], v[60:63]
	v_mfma_f32_16x16x32_bf16 v[52:55], v[158:161], v[184:187], v[52:55]
	v_mfma_f32_16x16x32_bf16 v[44:47], v[150:153], v[192:195], v[44:47]
	v_mfma_f32_16x16x32_bf16 v[36:39], v[158:161], v[192:195], v[36:39]
	v_mfma_f32_16x16x32_bf16 v[28:31], v[150:153], v[208:211], v[28:31]
	v_mfma_f32_16x16x32_bf16 v[20:23], v[158:161], v[208:211], v[20:23]
	v_mfma_f32_16x16x32_bf16 v[12:15], v[150:153], v[216:219], v[12:15]
	v_mfma_f32_16x16x32_bf16 v[4:7], v[158:161], v[216:219], v[4:7]
	v_mfma_f32_16x16x32_bf16 v[56:59], v[162:165], v[178:181], v[56:59]
	v_mfma_f32_16x16x32_bf16 v[48:51], v[170:173], v[178:181], v[48:51]
	v_mfma_f32_16x16x32_bf16 v[40:43], v[162:165], v[188:191], v[40:43]
	v_mfma_f32_16x16x32_bf16 v[32:35], v[170:173], v[188:191], v[32:35]
	v_mfma_f32_16x16x32_bf16 v[24:27], v[162:165], v[204:207], v[24:27]
	v_mfma_f32_16x16x32_bf16 v[16:19], v[170:173], v[204:207], v[16:19]
	v_mfma_f32_16x16x32_bf16 v[8:11], v[162:165], v[212:215], v[8:11]
	v_mfma_f32_16x16x32_bf16 v[0:3], v[170:173], v[212:215], v[0:3]
	v_mfma_f32_16x16x32_bf16 v[56:59], v[166:169], v[184:187], v[56:59]
	v_mfma_f32_16x16x32_bf16 v[48:51], v[174:177], v[184:187], v[48:51]
	v_mfma_f32_16x16x32_bf16 v[40:43], v[166:169], v[192:195], v[40:43]
	v_mfma_f32_16x16x32_bf16 v[32:35], v[174:177], v[192:195], v[32:35]
	v_mfma_f32_16x16x32_bf16 v[24:27], v[166:169], v[208:211], v[24:27]
	v_mfma_f32_16x16x32_bf16 v[16:19], v[174:177], v[208:211], v[16:19]
	v_mfma_f32_16x16x32_bf16 v[8:11], v[166:169], v[216:219], v[8:11]
	v_mfma_f32_16x16x32_bf16 v[0:3], v[174:177], v[216:219], v[0:3]
	s_setprio 0
	s_barrier
	s_add_u32 s76, s76, 0x100
	s_addc_u32 s77, s77, 0
	s_add_u32 s16, s16, 0x100
	s_addc_u32 s82, s82, 0
	s_cmp_ge_i32 s83, s47
	s_mov_b32 s78, s83
	s_cbranch_scc0 .LBB0_1042

.LBB0_1122:
	s_add_i32 s65, s55, 2
	s_add_u32 s44, s86, 0x80
	s_addc_u32 s45, s87, 0
	s_add_i32 s58, 0, 0x10000
	s_cmp_eq_u32 s29, s55
	s_cselect_b32 s89, s11, s45
	s_cselect_b32 s88, s10, s44
	v_add_u32_e32 v128, s58, v185
	s_cselect_b32 s45, s85, s54
	s_cselect_b32 s44, s84, s16
	s_add_i32 s55, 0, 0x14000
	ds_read_b128 v[130:133], v128
	ds_read_b128 v[134:137], v128 offset:1024
	ds_read_b128 v[138:141], v128 offset:2048
	ds_read_b128 v[142:145], v128 offset:3072
	v_add_u32_e32 v128, s55, v185
	ds_read_b128 v[146:149], v128
	ds_read_b128 v[150:153], v128 offset:1024
	ds_read_b128 v[166:169], v128 offset:2048
	ds_read_b128 v[170:173], v128 offset:3072
	v_lshl_add_u64 v[220:221], s[86:87], 0, v[162:163]
	s_add_i32 m0, s40, 0xc000
	ds_read_b128 v[174:177], v187
	ds_read_b128 v[178:181], v187 offset:1024
	ds_read_b128 v[188:191], v187 offset:2048
	ds_read_b128 v[192:195], v187 offset:3072
	ds_read_b128 v[204:207], v187 offset:4096
	ds_read_b128 v[208:211], v187 offset:5120
	ds_read_b128 v[212:215], v187 offset:6144
	ds_read_b128 v[216:219], v187 offset:7168
	global_load_lds_dwordx4 v[220:221], off
	v_lshl_add_u64 v[220:221], s[86:87], 0, v[164:165]
	s_add_i32 m0, s40, 0xe000
	s_nop 0
	global_load_lds_dwordx4 v[220:221], off
	s_waitcnt vmcnt(8)
	s_waitcnt lgkmcnt(0)
	s_barrier
	s_setprio 1
	s_waitcnt lgkmcnt(0)
	v_mfma_f32_16x16x32_bf16 v[124:127], v[130:133], v[174:177], v[124:127]
	v_mfma_f32_16x16x32_bf16 v[120:123], v[138:141], v[174:177], v[120:123]
	v_mfma_f32_16x16x32_bf16 v[108:111], v[130:133], v[188:191], v[108:111]
	v_mfma_f32_16x16x32_bf16 v[104:107], v[138:141], v[188:191], v[104:107]
	v_mfma_f32_16x16x32_bf16 v[92:95], v[130:133], v[204:207], v[92:95]
	v_mfma_f32_16x16x32_bf16 v[88:91], v[138:141], v[204:207], v[88:91]
	v_mfma_f32_16x16x32_bf16 v[76:79], v[130:133], v[212:215], v[76:79]
	v_mfma_f32_16x16x32_bf16 v[72:75], v[138:141], v[212:215], v[72:75]
	v_mfma_f32_16x16x32_bf16 v[124:127], v[134:137], v[178:181], v[124:127]
	v_mfma_f32_16x16x32_bf16 v[120:123], v[142:145], v[178:181], v[120:123]
	v_mfma_f32_16x16x32_bf16 v[108:111], v[134:137], v[192:195], v[108:111]
	v_mfma_f32_16x16x32_bf16 v[104:107], v[142:145], v[192:195], v[104:107]
	v_mfma_f32_16x16x32_bf16 v[92:95], v[134:137], v[208:211], v[92:95]
	v_mfma_f32_16x16x32_bf16 v[88:91], v[142:145], v[208:211], v[88:91]
	v_mfma_f32_16x16x32_bf16 v[76:79], v[134:137], v[216:219], v[76:79]
	v_mfma_f32_16x16x32_bf16 v[72:75], v[142:145], v[216:219], v[72:75]
	v_mfma_f32_16x16x32_bf16 v[116:119], v[146:149], v[174:177], v[116:119]
	v_mfma_f32_16x16x32_bf16 v[112:115], v[166:169], v[174:177], v[112:115]
	v_mfma_f32_16x16x32_bf16 v[100:103], v[146:149], v[188:191], v[100:103]
	v_mfma_f32_16x16x32_bf16 v[96:99], v[166:169], v[188:191], v[96:99]
	v_mfma_f32_16x16x32_bf16 v[84:87], v[146:149], v[204:207], v[84:87]
	v_mfma_f32_16x16x32_bf16 v[80:83], v[166:169], v[204:207], v[80:83]
	v_mfma_f32_16x16x32_bf16 v[68:71], v[146:149], v[212:215], v[68:71]
	v_mfma_f32_16x16x32_bf16 v[64:67], v[166:169], v[212:215], v[64:67]
	v_mfma_f32_16x16x32_bf16 v[116:119], v[150:153], v[178:181], v[116:119]
	v_mfma_f32_16x16x32_bf16 v[112:115], v[170:173], v[178:181], v[112:115]
	v_mfma_f32_16x16x32_bf16 v[100:103], v[150:153], v[192:195], v[100:103]
	v_mfma_f32_16x16x32_bf16 v[96:99], v[170:173], v[192:195], v[96:99]
	v_mfma_f32_16x16x32_bf16 v[84:87], v[150:153], v[208:211], v[84:87]
	v_mfma_f32_16x16x32_bf16 v[80:83], v[170:173], v[208:211], v[80:83]
	v_mfma_f32_16x16x32_bf16 v[68:71], v[150:153], v[216:219], v[68:71]
	v_mfma_f32_16x16x32_bf16 v[64:67], v[170:173], v[216:219], v[64:67]
	s_setprio 0
	s_barrier
	s_add_i32 s58, s58, s69
	v_lshl_add_u64 v[220:221], s[44:45], 0, v[158:159]
	s_mov_b32 m0, s58
	ds_read_b128 v[174:177], v187 offset:16384
	ds_read_b128 v[178:181], v187 offset:17408
	ds_read_b128 v[188:191], v187 offset:18432
	ds_read_b128 v[192:195], v187 offset:19456
	ds_read_b128 v[204:207], v187 offset:20480
	ds_read_b128 v[208:211], v187 offset:21504
	ds_read_b128 v[212:215], v187 offset:22528
	ds_read_b128 v[216:219], v187 offset:23552
	global_load_lds_dwordx4 v[220:221], off
	s_add_i32 m0, s58, 0x2000
	v_lshl_add_u64 v[222:223], s[44:45], 0, v[154:155]
	s_add_u32 s44, s44, s70
	s_addc_u32 s45, s45, s71
	s_add_i32 s55, s55, s69
	global_load_lds_dwordx4 v[222:223], off
	v_lshl_add_u64 v[224:225], s[44:45], 0, v[158:159]
	s_mov_b32 m0, s55
	v_lshl_add_u64 v[226:227], s[44:45], 0, v[154:155]
	global_load_lds_dwordx4 v[224:225], off
	s_add_i32 m0, s55, 0x2000
	v_lshl_add_u64 v[228:229], s[88:89], 0, v[160:161]
	global_load_lds_dwordx4 v[226:227], off
	s_mov_b32 m0, s40
	v_lshl_add_u64 v[230:231], s[88:89], 0, v[156:157]
	global_load_lds_dwordx4 v[228:229], off
	s_mov_b32 m0, s4
	s_nop 0
	global_load_lds_dwordx4 v[230:231], off
	s_waitcnt vmcnt(8)
	s_waitcnt lgkmcnt(0)
	s_barrier
	s_setprio 1
	s_waitcnt lgkmcnt(0)
	v_mfma_f32_16x16x32_bf16 v[60:63], v[130:133], v[174:177], v[60:63]
	v_mfma_f32_16x16x32_bf16 v[56:59], v[138:141], v[174:177], v[56:59]
	v_mfma_f32_16x16x32_bf16 v[44:47], v[130:133], v[188:191], v[44:47]
	v_mfma_f32_16x16x32_bf16 v[40:43], v[138:141], v[188:191], v[40:43]
	v_mfma_f32_16x16x32_bf16 v[28:31], v[130:133], v[204:207], v[28:31]
	v_mfma_f32_16x16x32_bf16 v[24:27], v[138:141], v[204:207], v[24:27]
	v_mfma_f32_16x16x32_bf16 v[12:15], v[130:133], v[212:215], v[12:15]
	v_mfma_f32_16x16x32_bf16 v[8:11], v[138:141], v[212:215], v[8:11]
	v_mfma_f32_16x16x32_bf16 v[60:63], v[134:137], v[178:181], v[60:63]
	v_mfma_f32_16x16x32_bf16 v[56:59], v[142:145], v[178:181], v[56:59]
	v_mfma_f32_16x16x32_bf16 v[44:47], v[134:137], v[192:195], v[44:47]
	v_mfma_f32_16x16x32_bf16 v[40:43], v[142:145], v[192:195], v[40:43]
	v_mfma_f32_16x16x32_bf16 v[28:31], v[134:137], v[208:211], v[28:31]
	v_mfma_f32_16x16x32_bf16 v[24:27], v[142:145], v[208:211], v[24:27]
	v_mfma_f32_16x16x32_bf16 v[12:15], v[134:137], v[216:219], v[12:15]
	v_mfma_f32_16x16x32_bf16 v[8:11], v[142:145], v[216:219], v[8:11]
	v_mfma_f32_16x16x32_bf16 v[52:55], v[146:149], v[174:177], v[52:55]
	v_mfma_f32_16x16x32_bf16 v[48:51], v[166:169], v[174:177], v[48:51]
	v_mfma_f32_16x16x32_bf16 v[36:39], v[146:149], v[188:191], v[36:39]
	v_mfma_f32_16x16x32_bf16 v[32:35], v[166:169], v[188:191], v[32:35]
	v_mfma_f32_16x16x32_bf16 v[20:23], v[146:149], v[204:207], v[20:23]
	v_mfma_f32_16x16x32_bf16 v[16:19], v[166:169], v[204:207], v[16:19]
	v_mfma_f32_16x16x32_bf16 v[4:7], v[146:149], v[212:215], v[4:7]
	v_mfma_f32_16x16x32_bf16 v[0:3], v[166:169], v[212:215], v[0:3]
	v_mfma_f32_16x16x32_bf16 v[52:55], v[150:153], v[178:181], v[52:55]
	v_mfma_f32_16x16x32_bf16 v[48:51], v[170:173], v[178:181], v[48:51]
	v_mfma_f32_16x16x32_bf16 v[36:39], v[150:153], v[192:195], v[36:39]
	v_mfma_f32_16x16x32_bf16 v[32:35], v[170:173], v[192:195], v[32:35]
	v_mfma_f32_16x16x32_bf16 v[20:23], v[150:153], v[208:211], v[20:23]
	v_mfma_f32_16x16x32_bf16 v[16:19], v[170:173], v[208:211], v[16:19]
	v_mfma_f32_16x16x32_bf16 v[4:7], v[150:153], v[216:219], v[4:7]
	v_mfma_f32_16x16x32_bf16 v[0:3], v[170:173], v[216:219], v[0:3]
	s_setprio 0
	s_barrier
	s_add_i32 s55, 0, 0x18000
	v_add_u32_e32 v128, s55, v185
	s_add_i32 s58, 0, 0x1c000
	ds_read_b128 v[130:133], v128
	ds_read_b128 v[134:137], v128 offset:1024
	ds_read_b128 v[138:141], v128 offset:2048
	ds_read_b128 v[142:145], v128 offset:3072
	v_add_u32_e32 v128, s58, v185
	ds_read_b128 v[146:149], v128
	ds_read_b128 v[150:153], v128 offset:1024
	ds_read_b128 v[166:169], v128 offset:2048
	ds_read_b128 v[170:173], v128 offset:3072
	s_add_u32 s44, s88, s70
	s_addc_u32 s45, s89, s71
	s_mov_b32 m0, s5
	v_lshl_add_u64 v[232:233], s[44:45], 0, v[160:161]
	ds_read_b128 v[174:177], v187 offset:32768
	ds_read_b128 v[178:181], v187 offset:33792
	ds_read_b128 v[188:191], v187 offset:34816
	ds_read_b128 v[192:195], v187 offset:35840
	ds_read_b128 v[204:207], v187 offset:36864
	ds_read_b128 v[208:211], v187 offset:37888
	ds_read_b128 v[212:215], v187 offset:38912
	ds_read_b128 v[216:219], v187 offset:39936
	global_load_lds_dwordx4 v[232:233], off
	v_lshl_add_u64 v[232:233], s[44:45], 0, v[156:157]
	s_mov_b32 m0, s12
	s_nop 0
	global_load_lds_dwordx4 v[232:233], off
	s_waitcnt vmcnt(8)
	s_waitcnt lgkmcnt(0)
	s_barrier
	s_setprio 1
	s_waitcnt lgkmcnt(0)
	v_mfma_f32_16x16x32_bf16 v[124:127], v[130:133], v[174:177], v[124:127]
	v_mfma_f32_16x16x32_bf16 v[120:123], v[138:141], v[174:177], v[120:123]
	v_mfma_f32_16x16x32_bf16 v[108:111], v[130:133], v[188:191], v[108:111]
	v_mfma_f32_16x16x32_bf16 v[104:107], v[138:141], v[188:191], v[104:107]
	v_mfma_f32_16x16x32_bf16 v[92:95], v[130:133], v[204:207], v[92:95]
	v_mfma_f32_16x16x32_bf16 v[88:91], v[138:141], v[204:207], v[88:91]
	v_mfma_f32_16x16x32_bf16 v[76:79], v[130:133], v[212:215], v[76:79]
	v_mfma_f32_16x16x32_bf16 v[72:75], v[138:141], v[212:215], v[72:75]
	v_mfma_f32_16x16x32_bf16 v[124:127], v[134:137], v[178:181], v[124:127]
	v_mfma_f32_16x16x32_bf16 v[120:123], v[142:145], v[178:181], v[120:123]
	v_mfma_f32_16x16x32_bf16 v[108:111], v[134:137], v[192:195], v[108:111]
	v_mfma_f32_16x16x32_bf16 v[104:107], v[142:145], v[192:195], v[104:107]
	v_mfma_f32_16x16x32_bf16 v[92:95], v[134:137], v[208:211], v[92:95]
	v_mfma_f32_16x16x32_bf16 v[88:91], v[142:145], v[208:211], v[88:91]
	v_mfma_f32_16x16x32_bf16 v[76:79], v[134:137], v[216:219], v[76:79]
	v_mfma_f32_16x16x32_bf16 v[72:75], v[142:145], v[216:219], v[72:75]
	v_mfma_f32_16x16x32_bf16 v[116:119], v[146:149], v[174:177], v[116:119]
	v_mfma_f32_16x16x32_bf16 v[112:115], v[166:169], v[174:177], v[112:115]
	v_mfma_f32_16x16x32_bf16 v[100:103], v[146:149], v[188:191], v[100:103]
	v_mfma_f32_16x16x32_bf16 v[96:99], v[166:169], v[188:191], v[96:99]
	v_mfma_f32_16x16x32_bf16 v[84:87], v[146:149], v[204:207], v[84:87]
	v_mfma_f32_16x16x32_bf16 v[80:83], v[166:169], v[204:207], v[80:83]
	v_mfma_f32_16x16x32_bf16 v[68:71], v[146:149], v[212:215], v[68:71]
	v_mfma_f32_16x16x32_bf16 v[64:67], v[166:169], v[212:215], v[64:67]
	v_mfma_f32_16x16x32_bf16 v[116:119], v[150:153], v[178:181], v[116:119]
	v_mfma_f32_16x16x32_bf16 v[112:115], v[170:173], v[178:181], v[112:115]
	v_mfma_f32_16x16x32_bf16 v[100:103], v[150:153], v[192:195], v[100:103]
	v_mfma_f32_16x16x32_bf16 v[96:99], v[170:173], v[192:195], v[96:99]
	v_mfma_f32_16x16x32_bf16 v[84:87], v[150:153], v[208:211], v[84:87]
	v_mfma_f32_16x16x32_bf16 v[80:83], v[170:173], v[208:211], v[80:83]
	v_mfma_f32_16x16x32_bf16 v[68:71], v[150:153], v[216:219], v[68:71]
	v_mfma_f32_16x16x32_bf16 v[64:67], v[170:173], v[216:219], v[64:67]
	s_setprio 0
	s_barrier
	s_add_i32 s44, s55, s69
	v_lshl_add_u64 v[220:221], v[220:221], 0, s[52:53]
	s_mov_b32 m0, s44
	ds_read_b128 v[174:177], v187 offset:49152
	ds_read_b128 v[178:181], v187 offset:50176
	ds_read_b128 v[188:191], v187 offset:51200
	ds_read_b128 v[192:195], v187 offset:52224
	ds_read_b128 v[204:207], v187 offset:53248
	ds_read_b128 v[208:211], v187 offset:54272
	ds_read_b128 v[212:215], v187 offset:55296
	ds_read_b128 v[216:219], v187 offset:56320
	global_load_lds_dwordx4 v[220:221], off
	v_lshl_add_u64 v[220:221], v[222:223], 0, s[52:53]
	s_add_i32 m0, s44, 0x2000
	s_add_i32 s44, s58, s69
	global_load_lds_dwordx4 v[220:221], off
	v_lshl_add_u64 v[220:221], v[224:225], 0, s[52:53]
	s_mov_b32 m0, s44
	s_nop 0
	global_load_lds_dwordx4 v[220:221], off
	v_lshl_add_u64 v[220:221], v[226:227], 0, s[52:53]
	s_add_i32 m0, s44, 0x2000
	s_nop 0
	global_load_lds_dwordx4 v[220:221], off
	v_lshl_add_u64 v[220:221], v[228:229], 0, s[52:53]
	s_mov_b32 m0, s22
	s_nop 0
	global_load_lds_dwordx4 v[220:221], off
	v_lshl_add_u64 v[220:221], v[230:231], 0, s[52:53]
	s_mov_b32 m0, s23
	s_nop 0
	global_load_lds_dwordx4 v[220:221], off
	s_waitcnt vmcnt(8)
	s_waitcnt lgkmcnt(0)
	s_barrier
	s_setprio 1
	s_waitcnt lgkmcnt(0)
	v_mfma_f32_16x16x32_bf16 v[60:63], v[130:133], v[174:177], v[60:63]
	v_mfma_f32_16x16x32_bf16 v[56:59], v[138:141], v[174:177], v[56:59]
	v_mfma_f32_16x16x32_bf16 v[44:47], v[130:133], v[188:191], v[44:47]
	v_mfma_f32_16x16x32_bf16 v[40:43], v[138:141], v[188:191], v[40:43]
	v_mfma_f32_16x16x32_bf16 v[28:31], v[130:133], v[204:207], v[28:31]
	v_mfma_f32_16x16x32_bf16 v[24:27], v[138:141], v[204:207], v[24:27]
	v_mfma_f32_16x16x32_bf16 v[12:15], v[130:133], v[212:215], v[12:15]
	v_mfma_f32_16x16x32_bf16 v[8:11], v[138:141], v[212:215], v[8:11]
	v_mfma_f32_16x16x32_bf16 v[60:63], v[134:137], v[178:181], v[60:63]
	v_mfma_f32_16x16x32_bf16 v[56:59], v[142:145], v[178:181], v[56:59]
	v_mfma_f32_16x16x32_bf16 v[44:47], v[134:137], v[192:195], v[44:47]
	v_mfma_f32_16x16x32_bf16 v[40:43], v[142:145], v[192:195], v[40:43]
	v_mfma_f32_16x16x32_bf16 v[28:31], v[134:137], v[208:211], v[28:31]
	v_mfma_f32_16x16x32_bf16 v[24:27], v[142:145], v[208:211], v[24:27]
	v_mfma_f32_16x16x32_bf16 v[12:15], v[134:137], v[216:219], v[12:15]
	v_mfma_f32_16x16x32_bf16 v[8:11], v[142:145], v[216:219], v[8:11]
	v_mfma_f32_16x16x32_bf16 v[52:55], v[146:149], v[174:177], v[52:55]
	v_mfma_f32_16x16x32_bf16 v[48:51], v[166:169], v[174:177], v[48:51]
	v_mfma_f32_16x16x32_bf16 v[36:39], v[146:149], v[188:191], v[36:39]
	v_mfma_f32_16x16x32_bf16 v[32:35], v[166:169], v[188:191], v[32:35]
	v_mfma_f32_16x16x32_bf16 v[20:23], v[146:149], v[204:207], v[20:23]
	v_mfma_f32_16x16x32_bf16 v[16:19], v[166:169], v[204:207], v[16:19]
	v_mfma_f32_16x16x32_bf16 v[4:7], v[146:149], v[212:215], v[4:7]
	v_mfma_f32_16x16x32_bf16 v[0:3], v[166:169], v[212:215], v[0:3]
	v_mfma_f32_16x16x32_bf16 v[52:55], v[150:153], v[178:181], v[52:55]
	v_mfma_f32_16x16x32_bf16 v[48:51], v[170:173], v[178:181], v[48:51]
	v_mfma_f32_16x16x32_bf16 v[36:39], v[150:153], v[192:195], v[36:39]
	v_mfma_f32_16x16x32_bf16 v[32:35], v[170:173], v[192:195], v[32:35]
	v_mfma_f32_16x16x32_bf16 v[20:23], v[150:153], v[208:211], v[20:23]
	v_mfma_f32_16x16x32_bf16 v[16:19], v[170:173], v[208:211], v[16:19]
	v_mfma_f32_16x16x32_bf16 v[4:7], v[150:153], v[216:219], v[4:7]
	v_mfma_f32_16x16x32_bf16 v[0:3], v[170:173], v[216:219], v[0:3]
	s_setprio 0
	s_barrier
	s_add_u32 s86, s86, 0x100
	s_addc_u32 s87, s87, 0
	s_add_u32 s16, s16, 0x100
	s_addc_u32 s54, s54, 0
	s_cmp_ge_i32 s65, s13
	s_mov_b32 s55, s65
	s_cbranch_scc0 .LBB0_1122

.LBB0_1165:
	s_add_i32 s84, s82, 2
	s_add_u32 s44, s80, 0x80
	s_addc_u32 s45, s81, 0
	s_add_i32 s58, 0, 0x10000
	s_cmp_eq_u32 s41, s82
	s_cselect_b32 s83, s11, s45
	s_cselect_b32 s82, s10, s44
	v_add_u32_e32 v128, s58, v185
	s_cselect_b32 s45, s79, s55
	s_cselect_b32 s44, s78, s16
	s_add_i32 s85, 0, 0x14000
	ds_read_b128 v[130:133], v128
	ds_read_b128 v[134:137], v128 offset:1024
	ds_read_b128 v[138:141], v128 offset:2048
	ds_read_b128 v[142:145], v128 offset:3072
	v_add_u32_e32 v128, s85, v185
	ds_read_b128 v[146:149], v128
	ds_read_b128 v[150:153], v128 offset:1024
	ds_read_b128 v[166:169], v128 offset:2048
	ds_read_b128 v[170:173], v128 offset:3072
	v_lshl_add_u64 v[220:221], s[80:81], 0, v[162:163]
	s_add_i32 m0, s4, 0xc000
	ds_read_b128 v[174:177], v187
	ds_read_b128 v[178:181], v187 offset:1024
	ds_read_b128 v[188:191], v187 offset:2048
	ds_read_b128 v[192:195], v187 offset:3072
	ds_read_b128 v[204:207], v187 offset:4096
	ds_read_b128 v[208:211], v187 offset:5120
	ds_read_b128 v[212:215], v187 offset:6144
	ds_read_b128 v[216:219], v187 offset:7168
	global_load_lds_dwordx4 v[220:221], off
	v_lshl_add_u64 v[220:221], s[80:81], 0, v[164:165]
	s_add_i32 m0, s4, 0xe000
	s_nop 0
	global_load_lds_dwordx4 v[220:221], off
	s_waitcnt vmcnt(8)
	s_waitcnt lgkmcnt(0)
	s_barrier
	s_setprio 1
	s_waitcnt lgkmcnt(0)
	v_mfma_f32_16x16x32_bf16 v[124:127], v[130:133], v[174:177], v[124:127]
	v_mfma_f32_16x16x32_bf16 v[120:123], v[138:141], v[174:177], v[120:123]
	v_mfma_f32_16x16x32_bf16 v[108:111], v[130:133], v[188:191], v[108:111]
	v_mfma_f32_16x16x32_bf16 v[104:107], v[138:141], v[188:191], v[104:107]
	v_mfma_f32_16x16x32_bf16 v[92:95], v[130:133], v[204:207], v[92:95]
	v_mfma_f32_16x16x32_bf16 v[88:91], v[138:141], v[204:207], v[88:91]
	v_mfma_f32_16x16x32_bf16 v[76:79], v[130:133], v[212:215], v[76:79]
	v_mfma_f32_16x16x32_bf16 v[72:75], v[138:141], v[212:215], v[72:75]
	v_mfma_f32_16x16x32_bf16 v[124:127], v[134:137], v[178:181], v[124:127]
	v_mfma_f32_16x16x32_bf16 v[120:123], v[142:145], v[178:181], v[120:123]
	v_mfma_f32_16x16x32_bf16 v[108:111], v[134:137], v[192:195], v[108:111]
	v_mfma_f32_16x16x32_bf16 v[104:107], v[142:145], v[192:195], v[104:107]
	v_mfma_f32_16x16x32_bf16 v[92:95], v[134:137], v[208:211], v[92:95]
	v_mfma_f32_16x16x32_bf16 v[88:91], v[142:145], v[208:211], v[88:91]
	v_mfma_f32_16x16x32_bf16 v[76:79], v[134:137], v[216:219], v[76:79]
	v_mfma_f32_16x16x32_bf16 v[72:75], v[142:145], v[216:219], v[72:75]
	v_mfma_f32_16x16x32_bf16 v[116:119], v[146:149], v[174:177], v[116:119]
	v_mfma_f32_16x16x32_bf16 v[112:115], v[166:169], v[174:177], v[112:115]
	v_mfma_f32_16x16x32_bf16 v[100:103], v[146:149], v[188:191], v[100:103]
	v_mfma_f32_16x16x32_bf16 v[96:99], v[166:169], v[188:191], v[96:99]
	v_mfma_f32_16x16x32_bf16 v[84:87], v[146:149], v[204:207], v[84:87]
	v_mfma_f32_16x16x32_bf16 v[80:83], v[166:169], v[204:207], v[80:83]
	v_mfma_f32_16x16x32_bf16 v[68:71], v[146:149], v[212:215], v[68:71]
	v_mfma_f32_16x16x32_bf16 v[64:67], v[166:169], v[212:215], v[64:67]
	v_mfma_f32_16x16x32_bf16 v[116:119], v[150:153], v[178:181], v[116:119]
	v_mfma_f32_16x16x32_bf16 v[112:115], v[170:173], v[178:181], v[112:115]
	v_mfma_f32_16x16x32_bf16 v[100:103], v[150:153], v[192:195], v[100:103]
	v_mfma_f32_16x16x32_bf16 v[96:99], v[170:173], v[192:195], v[96:99]
	v_mfma_f32_16x16x32_bf16 v[84:87], v[150:153], v[208:211], v[84:87]
	v_mfma_f32_16x16x32_bf16 v[80:83], v[170:173], v[208:211], v[80:83]
	v_mfma_f32_16x16x32_bf16 v[68:71], v[150:153], v[216:219], v[68:71]
	v_mfma_f32_16x16x32_bf16 v[64:67], v[170:173], v[216:219], v[64:67]
	s_setprio 0
	s_barrier
	s_add_i32 s58, s58, s40
	v_lshl_add_u64 v[220:221], s[44:45], 0, v[158:159]
	s_mov_b32 m0, s58
	ds_read_b128 v[174:177], v187 offset:16384
	ds_read_b128 v[178:181], v187 offset:17408
	ds_read_b128 v[188:191], v187 offset:18432
	ds_read_b128 v[192:195], v187 offset:19456
	ds_read_b128 v[204:207], v187 offset:20480
	ds_read_b128 v[208:211], v187 offset:21504
	ds_read_b128 v[212:215], v187 offset:22528
	ds_read_b128 v[216:219], v187 offset:23552
	global_load_lds_dwordx4 v[220:221], off
	s_add_i32 m0, s58, 0x2000
	v_lshl_add_u64 v[222:223], s[44:45], 0, v[154:155]
	s_add_u32 s44, s44, s70
	s_addc_u32 s45, s45, s71
	s_add_i32 s58, s85, s40
	global_load_lds_dwordx4 v[222:223], off
	v_lshl_add_u64 v[224:225], s[44:45], 0, v[158:159]
	s_mov_b32 m0, s58
	v_lshl_add_u64 v[226:227], s[44:45], 0, v[154:155]
	global_load_lds_dwordx4 v[224:225], off
	s_add_i32 m0, s58, 0x2000
	v_lshl_add_u64 v[228:229], s[82:83], 0, v[160:161]
	global_load_lds_dwordx4 v[226:227], off
	s_mov_b32 m0, s4
	v_lshl_add_u64 v[230:231], s[82:83], 0, v[156:157]
	global_load_lds_dwordx4 v[228:229], off
	s_mov_b32 m0, s5
	s_nop 0
	global_load_lds_dwordx4 v[230:231], off
	s_waitcnt vmcnt(8)
	s_waitcnt lgkmcnt(0)
	s_barrier
	s_setprio 1
	s_waitcnt lgkmcnt(0)
	v_mfma_f32_16x16x32_bf16 v[60:63], v[130:133], v[174:177], v[60:63]
	v_mfma_f32_16x16x32_bf16 v[56:59], v[138:141], v[174:177], v[56:59]
	v_mfma_f32_16x16x32_bf16 v[44:47], v[130:133], v[188:191], v[44:47]
	v_mfma_f32_16x16x32_bf16 v[40:43], v[138:141], v[188:191], v[40:43]
	v_mfma_f32_16x16x32_bf16 v[28:31], v[130:133], v[204:207], v[28:31]
	v_mfma_f32_16x16x32_bf16 v[24:27], v[138:141], v[204:207], v[24:27]
	v_mfma_f32_16x16x32_bf16 v[12:15], v[130:133], v[212:215], v[12:15]
	v_mfma_f32_16x16x32_bf16 v[8:11], v[138:141], v[212:215], v[8:11]
	v_mfma_f32_16x16x32_bf16 v[60:63], v[134:137], v[178:181], v[60:63]
	v_mfma_f32_16x16x32_bf16 v[56:59], v[142:145], v[178:181], v[56:59]
	v_mfma_f32_16x16x32_bf16 v[44:47], v[134:137], v[192:195], v[44:47]
	v_mfma_f32_16x16x32_bf16 v[40:43], v[142:145], v[192:195], v[40:43]
	v_mfma_f32_16x16x32_bf16 v[28:31], v[134:137], v[208:211], v[28:31]
	v_mfma_f32_16x16x32_bf16 v[24:27], v[142:145], v[208:211], v[24:27]
	v_mfma_f32_16x16x32_bf16 v[12:15], v[134:137], v[216:219], v[12:15]
	v_mfma_f32_16x16x32_bf16 v[8:11], v[142:145], v[216:219], v[8:11]
	v_mfma_f32_16x16x32_bf16 v[52:55], v[146:149], v[174:177], v[52:55]
	v_mfma_f32_16x16x32_bf16 v[48:51], v[166:169], v[174:177], v[48:51]
	v_mfma_f32_16x16x32_bf16 v[36:39], v[146:149], v[188:191], v[36:39]
	v_mfma_f32_16x16x32_bf16 v[32:35], v[166:169], v[188:191], v[32:35]
	v_mfma_f32_16x16x32_bf16 v[20:23], v[146:149], v[204:207], v[20:23]
	v_mfma_f32_16x16x32_bf16 v[16:19], v[166:169], v[204:207], v[16:19]
	v_mfma_f32_16x16x32_bf16 v[4:7], v[146:149], v[212:215], v[4:7]
	v_mfma_f32_16x16x32_bf16 v[0:3], v[166:169], v[212:215], v[0:3]
	v_mfma_f32_16x16x32_bf16 v[52:55], v[150:153], v[178:181], v[52:55]
	v_mfma_f32_16x16x32_bf16 v[48:51], v[170:173], v[178:181], v[48:51]
	v_mfma_f32_16x16x32_bf16 v[36:39], v[150:153], v[192:195], v[36:39]
	v_mfma_f32_16x16x32_bf16 v[32:35], v[170:173], v[192:195], v[32:35]
	v_mfma_f32_16x16x32_bf16 v[20:23], v[150:153], v[208:211], v[20:23]
	v_mfma_f32_16x16x32_bf16 v[16:19], v[170:173], v[208:211], v[16:19]
	v_mfma_f32_16x16x32_bf16 v[4:7], v[150:153], v[216:219], v[4:7]
	v_mfma_f32_16x16x32_bf16 v[0:3], v[170:173], v[216:219], v[0:3]
	s_setprio 0
	s_barrier
	s_add_i32 s58, 0, 0x18000
	v_add_u32_e32 v128, s58, v185
	s_add_i32 s85, 0, 0x1c000
	ds_read_b128 v[130:133], v128
	ds_read_b128 v[134:137], v128 offset:1024
	ds_read_b128 v[138:141], v128 offset:2048
	ds_read_b128 v[142:145], v128 offset:3072
	v_add_u32_e32 v128, s85, v185
	ds_read_b128 v[146:149], v128
	ds_read_b128 v[150:153], v128 offset:1024
	ds_read_b128 v[166:169], v128 offset:2048
	ds_read_b128 v[170:173], v128 offset:3072
	s_add_u32 s44, s82, s70
	s_addc_u32 s45, s83, s71
	s_mov_b32 m0, s12
	v_lshl_add_u64 v[232:233], s[44:45], 0, v[160:161]
	ds_read_b128 v[174:177], v187 offset:32768
	ds_read_b128 v[178:181], v187 offset:33792
	ds_read_b128 v[188:191], v187 offset:34816
	ds_read_b128 v[192:195], v187 offset:35840
	ds_read_b128 v[204:207], v187 offset:36864
	ds_read_b128 v[208:211], v187 offset:37888
	ds_read_b128 v[212:215], v187 offset:38912
	ds_read_b128 v[216:219], v187 offset:39936
	global_load_lds_dwordx4 v[232:233], off
	v_lshl_add_u64 v[232:233], s[44:45], 0, v[156:157]
	s_mov_b32 m0, s13
	s_nop 0
	global_load_lds_dwordx4 v[232:233], off
	s_waitcnt vmcnt(8)
	s_waitcnt lgkmcnt(0)
	s_barrier
	s_setprio 1
	s_waitcnt lgkmcnt(0)
	v_mfma_f32_16x16x32_bf16 v[124:127], v[130:133], v[174:177], v[124:127]
	v_mfma_f32_16x16x32_bf16 v[120:123], v[138:141], v[174:177], v[120:123]
	v_mfma_f32_16x16x32_bf16 v[108:111], v[130:133], v[188:191], v[108:111]
	v_mfma_f32_16x16x32_bf16 v[104:107], v[138:141], v[188:191], v[104:107]
	v_mfma_f32_16x16x32_bf16 v[92:95], v[130:133], v[204:207], v[92:95]
	v_mfma_f32_16x16x32_bf16 v[88:91], v[138:141], v[204:207], v[88:91]
	v_mfma_f32_16x16x32_bf16 v[76:79], v[130:133], v[212:215], v[76:79]
	v_mfma_f32_16x16x32_bf16 v[72:75], v[138:141], v[212:215], v[72:75]
	v_mfma_f32_16x16x32_bf16 v[124:127], v[134:137], v[178:181], v[124:127]
	v_mfma_f32_16x16x32_bf16 v[120:123], v[142:145], v[178:181], v[120:123]
	v_mfma_f32_16x16x32_bf16 v[108:111], v[134:137], v[192:195], v[108:111]
	v_mfma_f32_16x16x32_bf16 v[104:107], v[142:145], v[192:195], v[104:107]
	v_mfma_f32_16x16x32_bf16 v[92:95], v[134:137], v[208:211], v[92:95]
	v_mfma_f32_16x16x32_bf16 v[88:91], v[142:145], v[208:211], v[88:91]
	v_mfma_f32_16x16x32_bf16 v[76:79], v[134:137], v[216:219], v[76:79]
	v_mfma_f32_16x16x32_bf16 v[72:75], v[142:145], v[216:219], v[72:75]
	v_mfma_f32_16x16x32_bf16 v[116:119], v[146:149], v[174:177], v[116:119]
	v_mfma_f32_16x16x32_bf16 v[112:115], v[166:169], v[174:177], v[112:115]
	v_mfma_f32_16x16x32_bf16 v[100:103], v[146:149], v[188:191], v[100:103]
	v_mfma_f32_16x16x32_bf16 v[96:99], v[166:169], v[188:191], v[96:99]
	v_mfma_f32_16x16x32_bf16 v[84:87], v[146:149], v[204:207], v[84:87]
	v_mfma_f32_16x16x32_bf16 v[80:83], v[166:169], v[204:207], v[80:83]
	v_mfma_f32_16x16x32_bf16 v[68:71], v[146:149], v[212:215], v[68:71]
	v_mfma_f32_16x16x32_bf16 v[64:67], v[166:169], v[212:215], v[64:67]
	v_mfma_f32_16x16x32_bf16 v[116:119], v[150:153], v[178:181], v[116:119]
	v_mfma_f32_16x16x32_bf16 v[112:115], v[170:173], v[178:181], v[112:115]
	v_mfma_f32_16x16x32_bf16 v[100:103], v[150:153], v[192:195], v[100:103]
	v_mfma_f32_16x16x32_bf16 v[96:99], v[170:173], v[192:195], v[96:99]
	v_mfma_f32_16x16x32_bf16 v[84:87], v[150:153], v[208:211], v[84:87]
	v_mfma_f32_16x16x32_bf16 v[80:83], v[170:173], v[208:211], v[80:83]
	v_mfma_f32_16x16x32_bf16 v[68:71], v[150:153], v[216:219], v[68:71]
	v_mfma_f32_16x16x32_bf16 v[64:67], v[170:173], v[216:219], v[64:67]
	s_setprio 0
	s_barrier
	s_add_i32 s44, s58, s40
	v_lshl_add_u64 v[220:221], v[220:221], 0, s[52:53]
	s_mov_b32 m0, s44
	ds_read_b128 v[174:177], v187 offset:49152
	ds_read_b128 v[178:181], v187 offset:50176
	ds_read_b128 v[188:191], v187 offset:51200
	ds_read_b128 v[192:195], v187 offset:52224
	ds_read_b128 v[204:207], v187 offset:53248
	ds_read_b128 v[208:211], v187 offset:54272
	ds_read_b128 v[212:215], v187 offset:55296
	ds_read_b128 v[216:219], v187 offset:56320
	global_load_lds_dwordx4 v[220:221], off
	v_lshl_add_u64 v[220:221], v[222:223], 0, s[52:53]
	s_add_i32 m0, s44, 0x2000
	s_add_i32 s44, s85, s40
	global_load_lds_dwordx4 v[220:221], off
	v_lshl_add_u64 v[220:221], v[224:225], 0, s[52:53]
	s_mov_b32 m0, s44
	s_nop 0
	global_load_lds_dwordx4 v[220:221], off
	v_lshl_add_u64 v[220:221], v[226:227], 0, s[52:53]
	s_add_i32 m0, s44, 0x2000
	s_nop 0
	global_load_lds_dwordx4 v[220:221], off
	v_lshl_add_u64 v[220:221], v[228:229], 0, s[52:53]
	s_mov_b32 m0, s23
	s_nop 0
	global_load_lds_dwordx4 v[220:221], off
	v_lshl_add_u64 v[220:221], v[230:231], 0, s[52:53]
	s_mov_b32 m0, s29
	s_nop 0
	global_load_lds_dwordx4 v[220:221], off
	s_waitcnt vmcnt(8)
	s_waitcnt lgkmcnt(0)
	s_barrier
	s_setprio 1
	s_waitcnt lgkmcnt(0)
	v_mfma_f32_16x16x32_bf16 v[60:63], v[130:133], v[174:177], v[60:63]
	v_mfma_f32_16x16x32_bf16 v[56:59], v[138:141], v[174:177], v[56:59]
	v_mfma_f32_16x16x32_bf16 v[44:47], v[130:133], v[188:191], v[44:47]
	v_mfma_f32_16x16x32_bf16 v[40:43], v[138:141], v[188:191], v[40:43]
	v_mfma_f32_16x16x32_bf16 v[28:31], v[130:133], v[204:207], v[28:31]
	v_mfma_f32_16x16x32_bf16 v[24:27], v[138:141], v[204:207], v[24:27]
	v_mfma_f32_16x16x32_bf16 v[12:15], v[130:133], v[212:215], v[12:15]
	v_mfma_f32_16x16x32_bf16 v[8:11], v[138:141], v[212:215], v[8:11]
	v_mfma_f32_16x16x32_bf16 v[60:63], v[134:137], v[178:181], v[60:63]
	v_mfma_f32_16x16x32_bf16 v[56:59], v[142:145], v[178:181], v[56:59]
	v_mfma_f32_16x16x32_bf16 v[44:47], v[134:137], v[192:195], v[44:47]
	v_mfma_f32_16x16x32_bf16 v[40:43], v[142:145], v[192:195], v[40:43]
	v_mfma_f32_16x16x32_bf16 v[28:31], v[134:137], v[208:211], v[28:31]
	v_mfma_f32_16x16x32_bf16 v[24:27], v[142:145], v[208:211], v[24:27]
	v_mfma_f32_16x16x32_bf16 v[12:15], v[134:137], v[216:219], v[12:15]
	v_mfma_f32_16x16x32_bf16 v[8:11], v[142:145], v[216:219], v[8:11]
	v_mfma_f32_16x16x32_bf16 v[52:55], v[146:149], v[174:177], v[52:55]
	v_mfma_f32_16x16x32_bf16 v[48:51], v[166:169], v[174:177], v[48:51]
	v_mfma_f32_16x16x32_bf16 v[36:39], v[146:149], v[188:191], v[36:39]
	v_mfma_f32_16x16x32_bf16 v[32:35], v[166:169], v[188:191], v[32:35]
	v_mfma_f32_16x16x32_bf16 v[20:23], v[146:149], v[204:207], v[20:23]
	v_mfma_f32_16x16x32_bf16 v[16:19], v[166:169], v[204:207], v[16:19]
	v_mfma_f32_16x16x32_bf16 v[4:7], v[146:149], v[212:215], v[4:7]
	v_mfma_f32_16x16x32_bf16 v[0:3], v[166:169], v[212:215], v[0:3]
	v_mfma_f32_16x16x32_bf16 v[52:55], v[150:153], v[178:181], v[52:55]
	v_mfma_f32_16x16x32_bf16 v[48:51], v[170:173], v[178:181], v[48:51]
	v_mfma_f32_16x16x32_bf16 v[36:39], v[150:153], v[192:195], v[36:39]
	v_mfma_f32_16x16x32_bf16 v[32:35], v[170:173], v[192:195], v[32:35]
	v_mfma_f32_16x16x32_bf16 v[20:23], v[150:153], v[208:211], v[20:23]
	v_mfma_f32_16x16x32_bf16 v[16:19], v[170:173], v[208:211], v[16:19]
	v_mfma_f32_16x16x32_bf16 v[4:7], v[150:153], v[216:219], v[4:7]
	v_mfma_f32_16x16x32_bf16 v[0:3], v[170:173], v[216:219], v[0:3]
	s_setprio 0
	s_barrier
	s_add_u32 s80, s80, 0x100
	s_addc_u32 s81, s81, 0
	s_add_u32 s16, s16, 0x100
	s_addc_u32 s55, s55, 0
	s_cmp_ge_i32 s84, s22
	s_mov_b32 s82, s84
	s_cbranch_scc0 .LBB0_1165
